# speedup vs baseline: 1.0245x; 1.0039x over previous
; template <int RB, int EK, int D> __device__ __forceinline__ void rwkv_item_ws(const Params& p, int j, int s, int hd, int rq, char* shm_) {
;     ...
;     for (int ci = 0; ci < nch; ++ci) {
;       int chunk = d == 0 ? ci : nch - 1 - ci;
;       int buf = ci & 1;
;       const float* sr = arr(buf, 0); const float* sv = arr(buf, 1); const float* sk = arr(buf, 2);
;       const float* skk = arr(buf, 3); const float* sb = arr(buf, 4); const float* sw = arr(buf, 5);
;       f32x2 kkc_[NP], wc_[NP], bc_[NP], k2c_[NP], rc_[NP];
;       float vvc[RB];
;       auto ld = [&](int stp, f32x2* kk_, f32x2* w_, f32x2* b_, f32x2* k2_, f32x2* r_, float* vv_) {
;         int t = d == 0 ? stp : CH - 1 - stp;
;         int o = t * 64 + kq * EK;
; #pragma unroll
;         for (int e = 0; e < NP; ++e) {
;           kk_[e] = *reinterpret_cast<const f32x2*>(skk + o + 2 * e);
;           w_[e] = *reinterpret_cast<const f32x2*>(sw + o + 2 * e);
;           b_[e] = *reinterpret_cast<const f32x2*>(sb + o + 2 * e);
;           k2_[e] = *reinterpret_cast<const f32x2*>(sk + o + 2 * e);
;           r_[e] = *reinterpret_cast<const f32x2*>(sr + o + 2 * e);
;         }
; #pragma unroll
;         for (int rb = 0; rb < RB; ++rb) vv_[rb] = sv[t * 64 + row0 + rb];
;       };
;       ld(0, kkc_, wc_, bc_, k2c_, rc_, vvc);
;       float ys[CH][RB];
; #pragma unroll
;       for (int stp = 0; stp < CH; ++stp) {
;         f32x2 kkn_[NP], wn_[NP], bn_[NP], k2n_[NP], rn_[NP];
;         float vvn[RB];
;         ld(stp < CH - 1 ? stp + 1 : CH - 1, kkn_, wn_, bn_, k2n_, rn_, vvn);
; #pragma unroll
;         for (int rb = 0; rb < RB; ++rb) {
;           f32x2 acc2 = S[rb][0] * kkc_[0] + S[rb][1] * kkc_[1];
;           if constexpr (NP == 4) acc2 += S[rb][2] * kkc_[2] + S[rb][3] * kkc_[3];
;           float sa = reduce_row<LPR>(-(acc2[0] + acc2[1]));
;           f32x2 sa2 = {sa, sa}, vv2 = {vvc[rb], vvc[rb]};
; #pragma unroll
;           for (int e = 0; e < NP; ++e) S[rb][e] = S[rb][e] * wc_[e] + sa2 * bc_[e] + vv2 * k2c_[e];
;           f32x2 y2 = S[rb][0] * rc_[0] + S[rb][1] * rc_[1];
;           if constexpr (NP == 4) y2 += S[rb][2] * rc_[2] + S[rb][3] * rc_[3];
;           ys[stp][rb] = reduce_row<LPR>(y2[0] + y2[1]);
;         }
.LBB0_2082:
	s_bitcmp1_b32 s14, 0
	s_cselect_b32 s7, 0x6000, 0
	s_addk_i32 s7, 0x110
	v_lshl_add_u32 v34, v2, 2, s7
	v_add_u32_e32 v35, 0x1800, v34
	v_lshl_add_u32 v3, v0, 2, s7
	ds_read_b128 v[6:9], v3 offset:16128
	ds_read_b128 v[10:13], v3 offset:24320
	ds_read_b64 v[26:27], v34 offset:7936
	ds_read_b128 v[18:21], v3 offset:12032
	ds_read_b128 v[14:17], v3 offset:20224
	ds_read_b128 v[22:25], v3 offset:3840
	ds_read_b128 v[36:39], v3 offset:15872
	ds_read_b128 v[40:43], v3 offset:24064
	ds_read_b64 v[56:57], v34 offset:7680
	ds_read_b128 v[48:51], v3 offset:11776
	ds_read_b128 v[44:47], v3 offset:19968
	ds_read_b128 v[52:55], v3 offset:3584
	s_waitcnt lgkmcnt(6)
	v_pk_mul_f32 v[28:29], v[58:59], v[6:7] op_sel_hi:[1,0]
	v_pk_fma_f32 v[28:29], v[60:61], v[6:7], v[28:29] op_sel:[0,1,0]
	v_pk_fma_f32 v[28:29], v[62:63], v[8:9], v[28:29] op_sel_hi:[1,0,1]
	v_pk_fma_f32 v[28:29], v[64:65], v[8:9], v[28:29] op_sel:[0,1,0]
	v_pk_mul_f32 v[66:67], v[58:59], v[10:11] op_sel_hi:[1,0]
	v_pk_mul_f32 v[68:69], v[60:61], v[10:11] op_sel:[0,1]
	v_add_f32_dpp v28, v28, v28 quad_perm:[1,0,3,2] row_mask:0xf bank_mask:0xf bound_ctrl:1
	v_add_f32_dpp v29, v29, v29 quad_perm:[1,0,3,2] row_mask:0xf bank_mask:0xf bound_ctrl:1
	v_pk_mul_f32 v[70:71], v[62:63], v[12:13] op_sel_hi:[1,0]
	v_add_f32_dpp v28, v28, v28 quad_perm:[2,3,0,1] row_mask:0xf bank_mask:0xf bound_ctrl:1
	v_add_f32_dpp v29, v29, v29 quad_perm:[2,3,0,1] row_mask:0xf bank_mask:0xf bound_ctrl:1
	v_pk_mul_f32 v[72:73], v[64:65], v[12:13] op_sel:[0,1]
	v_add_f32_dpp v28, v28, v28 row_half_mirror row_mask:0xf bank_mask:0xf bound_ctrl:1
	v_add_f32_dpp v29, v29, v29 row_half_mirror row_mask:0xf bank_mask:0xf bound_ctrl:1
	v_pk_fma_f32 v[66:67], v[26:27], v[18:19], v[66:67] op_sel_hi:[1,0,1]
	v_add_f32_dpp v28, v28, v28 row_mirror row_mask:0xf bank_mask:0xf bound_ctrl:1
	v_add_f32_dpp v29, v29, v29 row_mirror row_mask:0xf bank_mask:0xf bound_ctrl:1
	v_pk_fma_f32 v[68:69], v[26:27], v[18:19], v[68:69] op_sel:[0,1,0]
	v_pk_fma_f32 v[70:71], v[26:27], v[20:21], v[70:71] op_sel_hi:[1,0,1]
	v_pk_fma_f32 v[72:73], v[26:27], v[20:21], v[72:73] op_sel:[0,1,0]
	v_pk_fma_f32 v[58:59], v[28:29], v[14:15], v[66:67] op_sel_hi:[1,0,1] neg_lo:[1,0,0] neg_hi:[1,0,0]
	v_pk_fma_f32 v[60:61], v[28:29], v[14:15], v[68:69] op_sel:[0,1,0] neg_lo:[1,0,0] neg_hi:[1,0,0]
	v_pk_fma_f32 v[62:63], v[28:29], v[16:17], v[70:71] op_sel_hi:[1,0,1] neg_lo:[1,0,0] neg_hi:[1,0,0]
	v_pk_fma_f32 v[64:65], v[28:29], v[16:17], v[72:73] op_sel:[0,1,0] neg_lo:[1,0,0] neg_hi:[1,0,0]
	v_pk_mul_f32 v[74:75], v[58:59], v[22:23] op_sel_hi:[1,0]
	v_pk_fma_f32 v[74:75], v[60:61], v[22:23], v[74:75] op_sel:[0,1,0]
	v_pk_fma_f32 v[74:75], v[62:63], v[24:25], v[74:75] op_sel_hi:[1,0,1]
	v_pk_fma_f32 v[74:75], v[64:65], v[24:25], v[74:75] op_sel:[0,1,0]
	ds_read_b128 v[6:9], v3 offset:15616
	ds_read_b128 v[10:13], v3 offset:23808
	ds_read_b64 v[26:27], v34 offset:7424
	ds_read_b128 v[18:21], v3 offset:11520
	ds_read_b128 v[14:17], v3 offset:19712
	ds_read_b128 v[22:25], v3 offset:3328
	s_waitcnt lgkmcnt(6)
	v_pk_mul_f32 v[28:29], v[58:59], v[36:37] op_sel_hi:[1,0]
	v_pk_fma_f32 v[28:29], v[60:61], v[36:37], v[28:29] op_sel:[0,1,0]
	v_pk_fma_f32 v[28:29], v[62:63], v[38:39], v[28:29] op_sel_hi:[1,0,1]
	v_pk_fma_f32 v[28:29], v[64:65], v[38:39], v[28:29] op_sel:[0,1,0]
	v_pk_mul_f32 v[66:67], v[58:59], v[40:41] op_sel_hi:[1,0]
	v_pk_mul_f32 v[68:69], v[60:61], v[40:41] op_sel:[0,1]
	v_add_f32_dpp v28, v28, v28 quad_perm:[1,0,3,2] row_mask:0xf bank_mask:0xf bound_ctrl:1
	v_add_f32_dpp v29, v29, v29 quad_perm:[1,0,3,2] row_mask:0xf bank_mask:0xf bound_ctrl:1
	v_pk_mul_f32 v[70:71], v[62:63], v[42:43] op_sel_hi:[1,0]
	v_add_f32_dpp v28, v28, v28 quad_perm:[2,3,0,1] row_mask:0xf bank_mask:0xf bound_ctrl:1
	v_add_f32_dpp v29, v29, v29 quad_perm:[2,3,0,1] row_mask:0xf bank_mask:0xf bound_ctrl:1
	v_pk_mul_f32 v[72:73], v[64:65], v[42:43] op_sel:[0,1]
	v_add_f32_dpp v28, v28, v28 row_half_mirror row_mask:0xf bank_mask:0xf bound_ctrl:1
	v_add_f32_dpp v29, v29, v29 row_half_mirror row_mask:0xf bank_mask:0xf bound_ctrl:1
	v_pk_fma_f32 v[66:67], v[56:57], v[48:49], v[66:67] op_sel_hi:[1,0,1]
	v_add_f32_dpp v28, v28, v28 row_mirror row_mask:0xf bank_mask:0xf bound_ctrl:1
	v_add_f32_dpp v29, v29, v29 row_mirror row_mask:0xf bank_mask:0xf bound_ctrl:1
	v_pk_fma_f32 v[68:69], v[56:57], v[48:49], v[68:69] op_sel:[0,1,0]
	v_pk_fma_f32 v[70:71], v[56:57], v[50:51], v[70:71] op_sel_hi:[1,0,1]
	v_pk_fma_f32 v[72:73], v[56:57], v[50:51], v[72:73] op_sel:[0,1,0]
	v_pk_fma_f32 v[58:59], v[28:29], v[44:45], v[66:67] op_sel_hi:[1,0,1] neg_lo:[1,0,0] neg_hi:[1,0,0]
	v_pk_fma_f32 v[60:61], v[28:29], v[44:45], v[68:69] op_sel:[0,1,0] neg_lo:[1,0,0] neg_hi:[1,0,0]
	v_pk_fma_f32 v[62:63], v[28:29], v[46:47], v[70:71] op_sel_hi:[1,0,1] neg_lo:[1,0,0] neg_hi:[1,0,0]
	v_pk_fma_f32 v[64:65], v[28:29], v[46:47], v[72:73] op_sel:[0,1,0] neg_lo:[1,0,0] neg_hi:[1,0,0]
	v_pk_mul_f32 v[76:77], v[58:59], v[52:53] op_sel_hi:[1,0]
	v_pk_fma_f32 v[76:77], v[60:61], v[52:53], v[76:77] op_sel:[0,1,0]
	v_pk_fma_f32 v[76:77], v[62:63], v[54:55], v[76:77] op_sel_hi:[1,0,1]
	v_pk_fma_f32 v[76:77], v[64:65], v[54:55], v[76:77] op_sel:[0,1,0]
	ds_read_b128 v[36:39], v3 offset:15360
	ds_read_b128 v[40:43], v3 offset:23552
	ds_read_b64 v[56:57], v34 offset:7168
	ds_read_b128 v[48:51], v3 offset:11264
	ds_read_b128 v[44:47], v3 offset:19456
	ds_read_b128 v[52:55], v3 offset:3072
	s_waitcnt lgkmcnt(6)
; template <int RB, int EK, int D> __device__ __forceinline__ void rwkv_item_ws(const Params& p, int j, int s, int hd, int rq, char* shm_) {
;     ...
;       auto ld = [&](int stp, f32x2* kk_, f32x2* w_, f32x2* b_, f32x2* k2_, f32x2* r_, float* vv_) {
;         int t = d == 0 ? stp : CH - 1 - stp;
;         int o = t * 64 + kq * EK;
; #pragma unroll
;         for (int e = 0; e < NP; ++e) {
;           kk_[e] = *reinterpret_cast<const f32x2*>(skk + o + 2 * e);
;           w_[e] = *reinterpret_cast<const f32x2*>(sw + o + 2 * e);
;           b_[e] = *reinterpret_cast<const f32x2*>(sb + o + 2 * e);
;           k2_[e] = *reinterpret_cast<const f32x2*>(sk + o + 2 * e);
;           r_[e] = *reinterpret_cast<const f32x2*>(sr + o + 2 * e);
;         }
; #pragma unroll
;         for (int rb = 0; rb < RB; ++rb) vv_[rb] = sv[t * 64 + row0 + rb];
;       };
;       ld(0, kkc_, wc_, bc_, k2c_, rc_, vvc);
;       float ys[CH][RB];
; #pragma unroll
;       for (int stp = 0; stp < CH; ++stp) {
;         f32x2 kkn_[NP], wn_[NP], bn_[NP], k2n_[NP], rn_[NP];
;         float vvn[RB];
;         ld(stp < CH - 1 ? stp + 1 : CH - 1, kkn_, wn_, bn_, k2n_, rn_, vvn);
; #pragma unroll
;         for (int rb = 0; rb < RB; ++rb) {
;           f32x2 acc2 = S[rb][0] * kkc_[0] + S[rb][1] * kkc_[1];
;           if constexpr (NP == 4) acc2 += S[rb][2] * kkc_[2] + S[rb][3] * kkc_[3];
;           float sa = reduce_row<LPR>(-(acc2[0] + acc2[1]));
;           f32x2 sa2 = {sa, sa}, vv2 = {vvc[rb], vvc[rb]};
; #pragma unroll
;           for (int e = 0; e < NP; ++e) S[rb][e] = S[rb][e] * wc_[e] + sa2 * bc_[e] + vv2 * k2c_[e];
;           f32x2 y2 = S[rb][0] * rc_[0] + S[rb][1] * rc_[1];
;           if constexpr (NP == 4) y2 += S[rb][2] * rc_[2] + S[rb][3] * rc_[3];
;           ys[stp][rb] = reduce_row<LPR>(y2[0] + y2[1]);
;         }
	v_pk_mul_f32 v[28:29], v[58:59], v[6:7] op_sel_hi:[1,0]
	v_pk_fma_f32 v[28:29], v[60:61], v[6:7], v[28:29] op_sel:[0,1,0]
	v_pk_fma_f32 v[28:29], v[62:63], v[8:9], v[28:29] op_sel_hi:[1,0,1]
	v_pk_fma_f32 v[28:29], v[64:65], v[8:9], v[28:29] op_sel:[0,1,0]
	v_pk_mul_f32 v[66:67], v[58:59], v[10:11] op_sel_hi:[1,0]
	v_pk_mul_f32 v[68:69], v[60:61], v[10:11] op_sel:[0,1]
	v_add_f32_dpp v28, v28, v28 quad_perm:[1,0,3,2] row_mask:0xf bank_mask:0xf bound_ctrl:1
	v_add_f32_dpp v29, v29, v29 quad_perm:[1,0,3,2] row_mask:0xf bank_mask:0xf bound_ctrl:1
	v_pk_mul_f32 v[70:71], v[62:63], v[12:13] op_sel_hi:[1,0]
	v_add_f32_dpp v28, v28, v28 quad_perm:[2,3,0,1] row_mask:0xf bank_mask:0xf bound_ctrl:1
	v_add_f32_dpp v29, v29, v29 quad_perm:[2,3,0,1] row_mask:0xf bank_mask:0xf bound_ctrl:1
	v_pk_mul_f32 v[72:73], v[64:65], v[12:13] op_sel:[0,1]
	v_add_f32_dpp v28, v28, v28 row_half_mirror row_mask:0xf bank_mask:0xf bound_ctrl:1
	v_add_f32_dpp v29, v29, v29 row_half_mirror row_mask:0xf bank_mask:0xf bound_ctrl:1
	v_pk_fma_f32 v[66:67], v[26:27], v[18:19], v[66:67] op_sel_hi:[1,0,1]
	v_add_f32_dpp v28, v28, v28 row_mirror row_mask:0xf bank_mask:0xf bound_ctrl:1
	v_add_f32_dpp v29, v29, v29 row_mirror row_mask:0xf bank_mask:0xf bound_ctrl:1
	v_pk_fma_f32 v[68:69], v[26:27], v[18:19], v[68:69] op_sel:[0,1,0]
	v_pk_fma_f32 v[70:71], v[26:27], v[20:21], v[70:71] op_sel_hi:[1,0,1]
	v_pk_fma_f32 v[72:73], v[26:27], v[20:21], v[72:73] op_sel:[0,1,0]
	v_pk_fma_f32 v[58:59], v[28:29], v[14:15], v[66:67] op_sel_hi:[1,0,1] neg_lo:[1,0,0] neg_hi:[1,0,0]
	v_pk_fma_f32 v[60:61], v[28:29], v[14:15], v[68:69] op_sel:[0,1,0] neg_lo:[1,0,0] neg_hi:[1,0,0]
	v_pk_fma_f32 v[62:63], v[28:29], v[16:17], v[70:71] op_sel_hi:[1,0,1] neg_lo:[1,0,0] neg_hi:[1,0,0]
	v_pk_fma_f32 v[64:65], v[28:29], v[16:17], v[72:73] op_sel:[0,1,0] neg_lo:[1,0,0] neg_hi:[1,0,0]
	v_pk_mul_f32 v[78:79], v[58:59], v[22:23] op_sel_hi:[1,0]
	v_pk_fma_f32 v[78:79], v[60:61], v[22:23], v[78:79] op_sel:[0,1,0]
	v_pk_fma_f32 v[78:79], v[62:63], v[24:25], v[78:79] op_sel_hi:[1,0,1]
	v_pk_fma_f32 v[78:79], v[64:65], v[24:25], v[78:79] op_sel:[0,1,0]
	ds_read_b128 v[6:9], v3 offset:15104
	ds_read_b128 v[10:13], v3 offset:23296
	ds_read_b64 v[26:27], v34 offset:6912
	ds_read_b128 v[18:21], v3 offset:11008
	ds_read_b128 v[14:17], v3 offset:19200
	ds_read_b128 v[22:25], v3 offset:2816
	s_waitcnt lgkmcnt(6)
	v_pk_mul_f32 v[28:29], v[58:59], v[36:37] op_sel_hi:[1,0]
	v_pk_fma_f32 v[28:29], v[60:61], v[36:37], v[28:29] op_sel:[0,1,0]
	v_pk_fma_f32 v[28:29], v[62:63], v[38:39], v[28:29] op_sel_hi:[1,0,1]
	v_pk_fma_f32 v[28:29], v[64:65], v[38:39], v[28:29] op_sel:[0,1,0]
	v_pk_mul_f32 v[66:67], v[58:59], v[40:41] op_sel_hi:[1,0]
	v_pk_mul_f32 v[68:69], v[60:61], v[40:41] op_sel:[0,1]
	v_add_f32_dpp v28, v28, v28 quad_perm:[1,0,3,2] row_mask:0xf bank_mask:0xf bound_ctrl:1
	v_add_f32_dpp v29, v29, v29 quad_perm:[1,0,3,2] row_mask:0xf bank_mask:0xf bound_ctrl:1
	v_pk_mul_f32 v[70:71], v[62:63], v[42:43] op_sel_hi:[1,0]
	v_add_f32_dpp v28, v28, v28 quad_perm:[2,3,0,1] row_mask:0xf bank_mask:0xf bound_ctrl:1
	v_add_f32_dpp v29, v29, v29 quad_perm:[2,3,0,1] row_mask:0xf bank_mask:0xf bound_ctrl:1
	v_pk_mul_f32 v[72:73], v[64:65], v[42:43] op_sel:[0,1]
	v_add_f32_dpp v28, v28, v28 row_half_mirror row_mask:0xf bank_mask:0xf bound_ctrl:1
	v_add_f32_dpp v29, v29, v29 row_half_mirror row_mask:0xf bank_mask:0xf bound_ctrl:1
	v_pk_fma_f32 v[66:67], v[56:57], v[48:49], v[66:67] op_sel_hi:[1,0,1]
	v_add_f32_dpp v28, v28, v28 row_mirror row_mask:0xf bank_mask:0xf bound_ctrl:1
	v_add_f32_dpp v29, v29, v29 row_mirror row_mask:0xf bank_mask:0xf bound_ctrl:1
	v_pk_fma_f32 v[68:69], v[56:57], v[48:49], v[68:69] op_sel:[0,1,0]
	v_pk_fma_f32 v[70:71], v[56:57], v[50:51], v[70:71] op_sel_hi:[1,0,1]
	v_pk_fma_f32 v[72:73], v[56:57], v[50:51], v[72:73] op_sel:[0,1,0]
	v_pk_fma_f32 v[58:59], v[28:29], v[44:45], v[66:67] op_sel_hi:[1,0,1] neg_lo:[1,0,0] neg_hi:[1,0,0]
	v_pk_fma_f32 v[60:61], v[28:29], v[44:45], v[68:69] op_sel:[0,1,0] neg_lo:[1,0,0] neg_hi:[1,0,0]
	v_pk_fma_f32 v[62:63], v[28:29], v[46:47], v[70:71] op_sel_hi:[1,0,1] neg_lo:[1,0,0] neg_hi:[1,0,0]
	v_pk_fma_f32 v[64:65], v[28:29], v[46:47], v[72:73] op_sel:[0,1,0] neg_lo:[1,0,0] neg_hi:[1,0,0]
	v_pk_mul_f32 v[80:81], v[58:59], v[52:53] op_sel_hi:[1,0]
	v_pk_fma_f32 v[80:81], v[60:61], v[52:53], v[80:81] op_sel:[0,1,0]
	v_pk_fma_f32 v[80:81], v[62:63], v[54:55], v[80:81] op_sel_hi:[1,0,1]
	v_pk_fma_f32 v[80:81], v[64:65], v[54:55], v[80:81] op_sel:[0,1,0]
	ds_read_b128 v[36:39], v3 offset:14848
	ds_read_b128 v[40:43], v3 offset:23040
	ds_read_b64 v[56:57], v34 offset:6656
	ds_read_b128 v[48:51], v3 offset:10752
	ds_read_b128 v[44:47], v3 offset:18944
	ds_read_b128 v[52:55], v3 offset:2560
	s_waitcnt lgkmcnt(6)
; template <int RB, int EK, int D> __device__ __forceinline__ void rwkv_item_ws(const Params& p, int j, int s, int hd, int rq, char* shm_) {
;     ...
;       auto ld = [&](int stp, f32x2* kk_, f32x2* w_, f32x2* b_, f32x2* k2_, f32x2* r_, float* vv_) {
;         int t = d == 0 ? stp : CH - 1 - stp;
;         int o = t * 64 + kq * EK;
; #pragma unroll
;         for (int e = 0; e < NP; ++e) {
;           kk_[e] = *reinterpret_cast<const f32x2*>(skk + o + 2 * e);
;           w_[e] = *reinterpret_cast<const f32x2*>(sw + o + 2 * e);
;           b_[e] = *reinterpret_cast<const f32x2*>(sb + o + 2 * e);
;           k2_[e] = *reinterpret_cast<const f32x2*>(sk + o + 2 * e);
;           r_[e] = *reinterpret_cast<const f32x2*>(sr + o + 2 * e);
;         }
; #pragma unroll
;         for (int rb = 0; rb < RB; ++rb) vv_[rb] = sv[t * 64 + row0 + rb];
;       };
;       ld(0, kkc_, wc_, bc_, k2c_, rc_, vvc);
;       float ys[CH][RB];
; #pragma unroll
;       for (int stp = 0; stp < CH; ++stp) {
;         f32x2 kkn_[NP], wn_[NP], bn_[NP], k2n_[NP], rn_[NP];
;         float vvn[RB];
;         ld(stp < CH - 1 ? stp + 1 : CH - 1, kkn_, wn_, bn_, k2n_, rn_, vvn);
; #pragma unroll
;         for (int rb = 0; rb < RB; ++rb) {
;           f32x2 acc2 = S[rb][0] * kkc_[0] + S[rb][1] * kkc_[1];
;           if constexpr (NP == 4) acc2 += S[rb][2] * kkc_[2] + S[rb][3] * kkc_[3];
;           float sa = reduce_row<LPR>(-(acc2[0] + acc2[1]));
;           f32x2 sa2 = {sa, sa}, vv2 = {vvc[rb], vvc[rb]};
; #pragma unroll
;           for (int e = 0; e < NP; ++e) S[rb][e] = S[rb][e] * wc_[e] + sa2 * bc_[e] + vv2 * k2c_[e];
;           f32x2 y2 = S[rb][0] * rc_[0] + S[rb][1] * rc_[1];
;           if constexpr (NP == 4) y2 += S[rb][2] * rc_[2] + S[rb][3] * rc_[3];
;           ys[stp][rb] = reduce_row<LPR>(y2[0] + y2[1]);
;         }
	v_pk_mul_f32 v[28:29], v[58:59], v[6:7] op_sel_hi:[1,0]
	v_pk_fma_f32 v[28:29], v[60:61], v[6:7], v[28:29] op_sel:[0,1,0]
	v_pk_fma_f32 v[28:29], v[62:63], v[8:9], v[28:29] op_sel_hi:[1,0,1]
	v_pk_fma_f32 v[28:29], v[64:65], v[8:9], v[28:29] op_sel:[0,1,0]
	v_pk_mul_f32 v[66:67], v[58:59], v[10:11] op_sel_hi:[1,0]
	v_pk_mul_f32 v[68:69], v[60:61], v[10:11] op_sel:[0,1]
	v_add_f32_dpp v28, v28, v28 quad_perm:[1,0,3,2] row_mask:0xf bank_mask:0xf bound_ctrl:1
	v_add_f32_dpp v29, v29, v29 quad_perm:[1,0,3,2] row_mask:0xf bank_mask:0xf bound_ctrl:1
	v_pk_mul_f32 v[70:71], v[62:63], v[12:13] op_sel_hi:[1,0]
	v_add_f32_dpp v28, v28, v28 quad_perm:[2,3,0,1] row_mask:0xf bank_mask:0xf bound_ctrl:1
	v_add_f32_dpp v29, v29, v29 quad_perm:[2,3,0,1] row_mask:0xf bank_mask:0xf bound_ctrl:1
	v_pk_mul_f32 v[72:73], v[64:65], v[12:13] op_sel:[0,1]
	v_add_f32_dpp v28, v28, v28 row_half_mirror row_mask:0xf bank_mask:0xf bound_ctrl:1
	v_add_f32_dpp v29, v29, v29 row_half_mirror row_mask:0xf bank_mask:0xf bound_ctrl:1
	v_pk_fma_f32 v[66:67], v[26:27], v[18:19], v[66:67] op_sel_hi:[1,0,1]
	v_add_f32_dpp v28, v28, v28 row_mirror row_mask:0xf bank_mask:0xf bound_ctrl:1
	v_add_f32_dpp v29, v29, v29 row_mirror row_mask:0xf bank_mask:0xf bound_ctrl:1
	v_pk_fma_f32 v[68:69], v[26:27], v[18:19], v[68:69] op_sel:[0,1,0]
	v_pk_fma_f32 v[70:71], v[26:27], v[20:21], v[70:71] op_sel_hi:[1,0,1]
	v_pk_fma_f32 v[72:73], v[26:27], v[20:21], v[72:73] op_sel:[0,1,0]
	v_pk_fma_f32 v[58:59], v[28:29], v[14:15], v[66:67] op_sel_hi:[1,0,1] neg_lo:[1,0,0] neg_hi:[1,0,0]
	v_pk_fma_f32 v[60:61], v[28:29], v[14:15], v[68:69] op_sel:[0,1,0] neg_lo:[1,0,0] neg_hi:[1,0,0]
	v_pk_fma_f32 v[62:63], v[28:29], v[16:17], v[70:71] op_sel_hi:[1,0,1] neg_lo:[1,0,0] neg_hi:[1,0,0]
	v_pk_fma_f32 v[64:65], v[28:29], v[16:17], v[72:73] op_sel:[0,1,0] neg_lo:[1,0,0] neg_hi:[1,0,0]
	v_pk_mul_f32 v[82:83], v[58:59], v[22:23] op_sel_hi:[1,0]
	v_pk_fma_f32 v[82:83], v[60:61], v[22:23], v[82:83] op_sel:[0,1,0]
	v_pk_fma_f32 v[82:83], v[62:63], v[24:25], v[82:83] op_sel_hi:[1,0,1]
	v_pk_fma_f32 v[82:83], v[64:65], v[24:25], v[82:83] op_sel:[0,1,0]
	ds_read_b128 v[6:9], v3 offset:14592
	ds_read_b128 v[10:13], v3 offset:22784
	ds_read_b64 v[26:27], v34 offset:6400
	ds_read_b128 v[18:21], v3 offset:10496
	ds_read_b128 v[14:17], v3 offset:18688
	ds_read_b128 v[22:25], v3 offset:2304
	s_waitcnt lgkmcnt(6)
	v_pk_mul_f32 v[28:29], v[58:59], v[36:37] op_sel_hi:[1,0]
	v_pk_fma_f32 v[28:29], v[60:61], v[36:37], v[28:29] op_sel:[0,1,0]
	v_pk_fma_f32 v[28:29], v[62:63], v[38:39], v[28:29] op_sel_hi:[1,0,1]
	v_pk_fma_f32 v[28:29], v[64:65], v[38:39], v[28:29] op_sel:[0,1,0]
	v_pk_mul_f32 v[66:67], v[58:59], v[40:41] op_sel_hi:[1,0]
	v_pk_mul_f32 v[68:69], v[60:61], v[40:41] op_sel:[0,1]
	v_add_f32_dpp v28, v28, v28 quad_perm:[1,0,3,2] row_mask:0xf bank_mask:0xf bound_ctrl:1
	v_add_f32_dpp v29, v29, v29 quad_perm:[1,0,3,2] row_mask:0xf bank_mask:0xf bound_ctrl:1
	v_pk_mul_f32 v[70:71], v[62:63], v[42:43] op_sel_hi:[1,0]
	v_add_f32_dpp v28, v28, v28 quad_perm:[2,3,0,1] row_mask:0xf bank_mask:0xf bound_ctrl:1
	v_add_f32_dpp v29, v29, v29 quad_perm:[2,3,0,1] row_mask:0xf bank_mask:0xf bound_ctrl:1
	v_pk_mul_f32 v[72:73], v[64:65], v[42:43] op_sel:[0,1]
	v_add_f32_dpp v28, v28, v28 row_half_mirror row_mask:0xf bank_mask:0xf bound_ctrl:1
	v_add_f32_dpp v29, v29, v29 row_half_mirror row_mask:0xf bank_mask:0xf bound_ctrl:1
	v_pk_fma_f32 v[66:67], v[56:57], v[48:49], v[66:67] op_sel_hi:[1,0,1]
	v_add_f32_dpp v28, v28, v28 row_mirror row_mask:0xf bank_mask:0xf bound_ctrl:1
	v_add_f32_dpp v29, v29, v29 row_mirror row_mask:0xf bank_mask:0xf bound_ctrl:1
	v_pk_fma_f32 v[68:69], v[56:57], v[48:49], v[68:69] op_sel:[0,1,0]
	v_pk_fma_f32 v[70:71], v[56:57], v[50:51], v[70:71] op_sel_hi:[1,0,1]
	v_pk_fma_f32 v[72:73], v[56:57], v[50:51], v[72:73] op_sel:[0,1,0]
	v_pk_fma_f32 v[58:59], v[28:29], v[44:45], v[66:67] op_sel_hi:[1,0,1] neg_lo:[1,0,0] neg_hi:[1,0,0]
	v_pk_fma_f32 v[60:61], v[28:29], v[44:45], v[68:69] op_sel:[0,1,0] neg_lo:[1,0,0] neg_hi:[1,0,0]
	v_pk_fma_f32 v[62:63], v[28:29], v[46:47], v[70:71] op_sel_hi:[1,0,1] neg_lo:[1,0,0] neg_hi:[1,0,0]
	v_pk_fma_f32 v[64:65], v[28:29], v[46:47], v[72:73] op_sel:[0,1,0] neg_lo:[1,0,0] neg_hi:[1,0,0]
	v_pk_mul_f32 v[84:85], v[58:59], v[52:53] op_sel_hi:[1,0]
	v_pk_fma_f32 v[84:85], v[60:61], v[52:53], v[84:85] op_sel:[0,1,0]
	v_pk_fma_f32 v[84:85], v[62:63], v[54:55], v[84:85] op_sel_hi:[1,0,1]
	v_pk_fma_f32 v[84:85], v[64:65], v[54:55], v[84:85] op_sel:[0,1,0]
	ds_read_b128 v[36:39], v3 offset:14336
	ds_read_b128 v[40:43], v3 offset:22528
	ds_read_b64 v[56:57], v34 offset:6144
	ds_read_b128 v[48:51], v3 offset:10240
	ds_read_b128 v[44:47], v3 offset:18432
	ds_read_b128 v[52:55], v3 offset:2048
	s_waitcnt lgkmcnt(6)
; template <int RB, int EK, int D> __device__ __forceinline__ void rwkv_item_ws(const Params& p, int j, int s, int hd, int rq, char* shm_) {
;     ...
;       auto ld = [&](int stp, f32x2* kk_, f32x2* w_, f32x2* b_, f32x2* k2_, f32x2* r_, float* vv_) {
;         int t = d == 0 ? stp : CH - 1 - stp;
;         int o = t * 64 + kq * EK;
; #pragma unroll
;         for (int e = 0; e < NP; ++e) {
;           kk_[e] = *reinterpret_cast<const f32x2*>(skk + o + 2 * e);
;           w_[e] = *reinterpret_cast<const f32x2*>(sw + o + 2 * e);
;           b_[e] = *reinterpret_cast<const f32x2*>(sb + o + 2 * e);
;           k2_[e] = *reinterpret_cast<const f32x2*>(sk + o + 2 * e);
;           r_[e] = *reinterpret_cast<const f32x2*>(sr + o + 2 * e);
;         }
; #pragma unroll
;         for (int rb = 0; rb < RB; ++rb) vv_[rb] = sv[t * 64 + row0 + rb];
;       };
;       ld(0, kkc_, wc_, bc_, k2c_, rc_, vvc);
;       float ys[CH][RB];
; #pragma unroll
;       for (int stp = 0; stp < CH; ++stp) {
;         f32x2 kkn_[NP], wn_[NP], bn_[NP], k2n_[NP], rn_[NP];
;         float vvn[RB];
;         ld(stp < CH - 1 ? stp + 1 : CH - 1, kkn_, wn_, bn_, k2n_, rn_, vvn);
; #pragma unroll
;         for (int rb = 0; rb < RB; ++rb) {
;           f32x2 acc2 = S[rb][0] * kkc_[0] + S[rb][1] * kkc_[1];
;           if constexpr (NP == 4) acc2 += S[rb][2] * kkc_[2] + S[rb][3] * kkc_[3];
;           float sa = reduce_row<LPR>(-(acc2[0] + acc2[1]));
;           f32x2 sa2 = {sa, sa}, vv2 = {vvc[rb], vvc[rb]};
; #pragma unroll
;           for (int e = 0; e < NP; ++e) S[rb][e] = S[rb][e] * wc_[e] + sa2 * bc_[e] + vv2 * k2c_[e];
;           f32x2 y2 = S[rb][0] * rc_[0] + S[rb][1] * rc_[1];
;           if constexpr (NP == 4) y2 += S[rb][2] * rc_[2] + S[rb][3] * rc_[3];
;           ys[stp][rb] = reduce_row<LPR>(y2[0] + y2[1]);
;         }
	v_pk_mul_f32 v[28:29], v[58:59], v[6:7] op_sel_hi:[1,0]
	v_pk_fma_f32 v[28:29], v[60:61], v[6:7], v[28:29] op_sel:[0,1,0]
	v_pk_fma_f32 v[28:29], v[62:63], v[8:9], v[28:29] op_sel_hi:[1,0,1]
	v_pk_fma_f32 v[28:29], v[64:65], v[8:9], v[28:29] op_sel:[0,1,0]
	v_pk_mul_f32 v[66:67], v[58:59], v[10:11] op_sel_hi:[1,0]
	v_pk_mul_f32 v[68:69], v[60:61], v[10:11] op_sel:[0,1]
	v_add_f32_dpp v28, v28, v28 quad_perm:[1,0,3,2] row_mask:0xf bank_mask:0xf bound_ctrl:1
	v_add_f32_dpp v29, v29, v29 quad_perm:[1,0,3,2] row_mask:0xf bank_mask:0xf bound_ctrl:1
	v_pk_mul_f32 v[70:71], v[62:63], v[12:13] op_sel_hi:[1,0]
	v_add_f32_dpp v28, v28, v28 quad_perm:[2,3,0,1] row_mask:0xf bank_mask:0xf bound_ctrl:1
	v_add_f32_dpp v29, v29, v29 quad_perm:[2,3,0,1] row_mask:0xf bank_mask:0xf bound_ctrl:1
	v_pk_mul_f32 v[72:73], v[64:65], v[12:13] op_sel:[0,1]
	v_add_f32_dpp v28, v28, v28 row_half_mirror row_mask:0xf bank_mask:0xf bound_ctrl:1
	v_add_f32_dpp v29, v29, v29 row_half_mirror row_mask:0xf bank_mask:0xf bound_ctrl:1
	v_pk_fma_f32 v[66:67], v[26:27], v[18:19], v[66:67] op_sel_hi:[1,0,1]
	v_add_f32_dpp v28, v28, v28 row_mirror row_mask:0xf bank_mask:0xf bound_ctrl:1
	v_add_f32_dpp v29, v29, v29 row_mirror row_mask:0xf bank_mask:0xf bound_ctrl:1
	v_pk_fma_f32 v[68:69], v[26:27], v[18:19], v[68:69] op_sel:[0,1,0]
	v_pk_fma_f32 v[70:71], v[26:27], v[20:21], v[70:71] op_sel_hi:[1,0,1]
	v_pk_fma_f32 v[72:73], v[26:27], v[20:21], v[72:73] op_sel:[0,1,0]
	v_pk_fma_f32 v[58:59], v[28:29], v[14:15], v[66:67] op_sel_hi:[1,0,1] neg_lo:[1,0,0] neg_hi:[1,0,0]
	v_pk_fma_f32 v[60:61], v[28:29], v[14:15], v[68:69] op_sel:[0,1,0] neg_lo:[1,0,0] neg_hi:[1,0,0]
	v_pk_fma_f32 v[62:63], v[28:29], v[16:17], v[70:71] op_sel_hi:[1,0,1] neg_lo:[1,0,0] neg_hi:[1,0,0]
	v_pk_fma_f32 v[64:65], v[28:29], v[16:17], v[72:73] op_sel:[0,1,0] neg_lo:[1,0,0] neg_hi:[1,0,0]
	v_pk_mul_f32 v[86:87], v[58:59], v[22:23] op_sel_hi:[1,0]
	v_pk_fma_f32 v[86:87], v[60:61], v[22:23], v[86:87] op_sel:[0,1,0]
	v_pk_fma_f32 v[86:87], v[62:63], v[24:25], v[86:87] op_sel_hi:[1,0,1]
	v_pk_fma_f32 v[86:87], v[64:65], v[24:25], v[86:87] op_sel:[0,1,0]
	ds_read_b128 v[6:9], v3 offset:14080
	ds_read_b128 v[10:13], v3 offset:22272
	ds_read_b64 v[26:27], v34 offset:5888
	ds_read_b128 v[18:21], v3 offset:9984
	ds_read_b128 v[14:17], v3 offset:18176
	ds_read_b128 v[22:25], v3 offset:1792
	s_waitcnt lgkmcnt(6)
	v_pk_mul_f32 v[28:29], v[58:59], v[36:37] op_sel_hi:[1,0]
	v_pk_fma_f32 v[28:29], v[60:61], v[36:37], v[28:29] op_sel:[0,1,0]
	v_pk_fma_f32 v[28:29], v[62:63], v[38:39], v[28:29] op_sel_hi:[1,0,1]
	v_pk_fma_f32 v[28:29], v[64:65], v[38:39], v[28:29] op_sel:[0,1,0]
	v_pk_mul_f32 v[66:67], v[58:59], v[40:41] op_sel_hi:[1,0]
	v_pk_mul_f32 v[68:69], v[60:61], v[40:41] op_sel:[0,1]
	v_add_f32_dpp v28, v28, v28 quad_perm:[1,0,3,2] row_mask:0xf bank_mask:0xf bound_ctrl:1
	v_add_f32_dpp v29, v29, v29 quad_perm:[1,0,3,2] row_mask:0xf bank_mask:0xf bound_ctrl:1
	v_pk_mul_f32 v[70:71], v[62:63], v[42:43] op_sel_hi:[1,0]
	v_add_f32_dpp v28, v28, v28 quad_perm:[2,3,0,1] row_mask:0xf bank_mask:0xf bound_ctrl:1
	v_add_f32_dpp v29, v29, v29 quad_perm:[2,3,0,1] row_mask:0xf bank_mask:0xf bound_ctrl:1
	v_pk_mul_f32 v[72:73], v[64:65], v[42:43] op_sel:[0,1]
	v_add_f32_dpp v28, v28, v28 row_half_mirror row_mask:0xf bank_mask:0xf bound_ctrl:1
	v_add_f32_dpp v29, v29, v29 row_half_mirror row_mask:0xf bank_mask:0xf bound_ctrl:1
	v_pk_fma_f32 v[66:67], v[56:57], v[48:49], v[66:67] op_sel_hi:[1,0,1]
	v_add_f32_dpp v28, v28, v28 row_mirror row_mask:0xf bank_mask:0xf bound_ctrl:1
	v_add_f32_dpp v29, v29, v29 row_mirror row_mask:0xf bank_mask:0xf bound_ctrl:1
	v_pk_fma_f32 v[68:69], v[56:57], v[48:49], v[68:69] op_sel:[0,1,0]
	v_pk_fma_f32 v[70:71], v[56:57], v[50:51], v[70:71] op_sel_hi:[1,0,1]
	v_pk_fma_f32 v[72:73], v[56:57], v[50:51], v[72:73] op_sel:[0,1,0]
	v_pk_fma_f32 v[58:59], v[28:29], v[44:45], v[66:67] op_sel_hi:[1,0,1] neg_lo:[1,0,0] neg_hi:[1,0,0]
	v_pk_fma_f32 v[60:61], v[28:29], v[44:45], v[68:69] op_sel:[0,1,0] neg_lo:[1,0,0] neg_hi:[1,0,0]
	v_pk_fma_f32 v[62:63], v[28:29], v[46:47], v[70:71] op_sel_hi:[1,0,1] neg_lo:[1,0,0] neg_hi:[1,0,0]
	v_pk_fma_f32 v[64:65], v[28:29], v[46:47], v[72:73] op_sel:[0,1,0] neg_lo:[1,0,0] neg_hi:[1,0,0]
	v_pk_mul_f32 v[88:89], v[58:59], v[52:53] op_sel_hi:[1,0]
	v_pk_fma_f32 v[88:89], v[60:61], v[52:53], v[88:89] op_sel:[0,1,0]
	v_pk_fma_f32 v[88:89], v[62:63], v[54:55], v[88:89] op_sel_hi:[1,0,1]
	v_pk_fma_f32 v[88:89], v[64:65], v[54:55], v[88:89] op_sel:[0,1,0]
	ds_read_b128 v[36:39], v3 offset:13824
	ds_read_b128 v[40:43], v3 offset:22016
	ds_read_b64 v[56:57], v34 offset:5632
	ds_read_b128 v[48:51], v3 offset:9728
	ds_read_b128 v[44:47], v3 offset:17920
	ds_read_b128 v[52:55], v3 offset:1536
	s_waitcnt lgkmcnt(6)
; template <int RB, int EK, int D> __device__ __forceinline__ void rwkv_item_ws(const Params& p, int j, int s, int hd, int rq, char* shm_) {
;     ...
;       auto ld = [&](int stp, f32x2* kk_, f32x2* w_, f32x2* b_, f32x2* k2_, f32x2* r_, float* vv_) {
;         int t = d == 0 ? stp : CH - 1 - stp;
;         int o = t * 64 + kq * EK;
; #pragma unroll
;         for (int e = 0; e < NP; ++e) {
;           kk_[e] = *reinterpret_cast<const f32x2*>(skk + o + 2 * e);
;           w_[e] = *reinterpret_cast<const f32x2*>(sw + o + 2 * e);
;           b_[e] = *reinterpret_cast<const f32x2*>(sb + o + 2 * e);
;           k2_[e] = *reinterpret_cast<const f32x2*>(sk + o + 2 * e);
;           r_[e] = *reinterpret_cast<const f32x2*>(sr + o + 2 * e);
;         }
; #pragma unroll
;         for (int rb = 0; rb < RB; ++rb) vv_[rb] = sv[t * 64 + row0 + rb];
;       };
;       ld(0, kkc_, wc_, bc_, k2c_, rc_, vvc);
;       float ys[CH][RB];
; #pragma unroll
;       for (int stp = 0; stp < CH; ++stp) {
;         f32x2 kkn_[NP], wn_[NP], bn_[NP], k2n_[NP], rn_[NP];
;         float vvn[RB];
;         ld(stp < CH - 1 ? stp + 1 : CH - 1, kkn_, wn_, bn_, k2n_, rn_, vvn);
; #pragma unroll
;         for (int rb = 0; rb < RB; ++rb) {
;           f32x2 acc2 = S[rb][0] * kkc_[0] + S[rb][1] * kkc_[1];
;           if constexpr (NP == 4) acc2 += S[rb][2] * kkc_[2] + S[rb][3] * kkc_[3];
;           float sa = reduce_row<LPR>(-(acc2[0] + acc2[1]));
;           f32x2 sa2 = {sa, sa}, vv2 = {vvc[rb], vvc[rb]};
; #pragma unroll
;           for (int e = 0; e < NP; ++e) S[rb][e] = S[rb][e] * wc_[e] + sa2 * bc_[e] + vv2 * k2c_[e];
;           f32x2 y2 = S[rb][0] * rc_[0] + S[rb][1] * rc_[1];
;           if constexpr (NP == 4) y2 += S[rb][2] * rc_[2] + S[rb][3] * rc_[3];
;           ys[stp][rb] = reduce_row<LPR>(y2[0] + y2[1]);
;         }
	v_pk_mul_f32 v[28:29], v[58:59], v[6:7] op_sel_hi:[1,0]
	v_pk_fma_f32 v[28:29], v[60:61], v[6:7], v[28:29] op_sel:[0,1,0]
	v_pk_fma_f32 v[28:29], v[62:63], v[8:9], v[28:29] op_sel_hi:[1,0,1]
	v_pk_fma_f32 v[28:29], v[64:65], v[8:9], v[28:29] op_sel:[0,1,0]
	v_pk_mul_f32 v[66:67], v[58:59], v[10:11] op_sel_hi:[1,0]
	v_pk_mul_f32 v[68:69], v[60:61], v[10:11] op_sel:[0,1]
	v_add_f32_dpp v28, v28, v28 quad_perm:[1,0,3,2] row_mask:0xf bank_mask:0xf bound_ctrl:1
	v_add_f32_dpp v29, v29, v29 quad_perm:[1,0,3,2] row_mask:0xf bank_mask:0xf bound_ctrl:1
	v_pk_mul_f32 v[70:71], v[62:63], v[12:13] op_sel_hi:[1,0]
	v_add_f32_dpp v28, v28, v28 quad_perm:[2,3,0,1] row_mask:0xf bank_mask:0xf bound_ctrl:1
	v_add_f32_dpp v29, v29, v29 quad_perm:[2,3,0,1] row_mask:0xf bank_mask:0xf bound_ctrl:1
	v_pk_mul_f32 v[72:73], v[64:65], v[12:13] op_sel:[0,1]
	v_add_f32_dpp v28, v28, v28 row_half_mirror row_mask:0xf bank_mask:0xf bound_ctrl:1
	v_add_f32_dpp v29, v29, v29 row_half_mirror row_mask:0xf bank_mask:0xf bound_ctrl:1
	v_pk_fma_f32 v[66:67], v[26:27], v[18:19], v[66:67] op_sel_hi:[1,0,1]
	v_add_f32_dpp v28, v28, v28 row_mirror row_mask:0xf bank_mask:0xf bound_ctrl:1
	v_add_f32_dpp v29, v29, v29 row_mirror row_mask:0xf bank_mask:0xf bound_ctrl:1
	v_pk_fma_f32 v[68:69], v[26:27], v[18:19], v[68:69] op_sel:[0,1,0]
	v_pk_fma_f32 v[70:71], v[26:27], v[20:21], v[70:71] op_sel_hi:[1,0,1]
	v_pk_fma_f32 v[72:73], v[26:27], v[20:21], v[72:73] op_sel:[0,1,0]
	v_pk_fma_f32 v[58:59], v[28:29], v[14:15], v[66:67] op_sel_hi:[1,0,1] neg_lo:[1,0,0] neg_hi:[1,0,0]
	v_pk_fma_f32 v[60:61], v[28:29], v[14:15], v[68:69] op_sel:[0,1,0] neg_lo:[1,0,0] neg_hi:[1,0,0]
	v_pk_fma_f32 v[62:63], v[28:29], v[16:17], v[70:71] op_sel_hi:[1,0,1] neg_lo:[1,0,0] neg_hi:[1,0,0]
	v_pk_fma_f32 v[64:65], v[28:29], v[16:17], v[72:73] op_sel:[0,1,0] neg_lo:[1,0,0] neg_hi:[1,0,0]
	v_pk_mul_f32 v[90:91], v[58:59], v[22:23] op_sel_hi:[1,0]
	v_pk_fma_f32 v[90:91], v[60:61], v[22:23], v[90:91] op_sel:[0,1,0]
	v_pk_fma_f32 v[90:91], v[62:63], v[24:25], v[90:91] op_sel_hi:[1,0,1]
	v_pk_fma_f32 v[90:91], v[64:65], v[24:25], v[90:91] op_sel:[0,1,0]
	ds_read_b128 v[6:9], v3 offset:13568
	ds_read_b128 v[10:13], v3 offset:21760
	ds_read_b64 v[26:27], v34 offset:5376
	ds_read_b128 v[18:21], v3 offset:9472
	ds_read_b128 v[14:17], v3 offset:17664
	ds_read_b128 v[22:25], v3 offset:1280
	s_waitcnt lgkmcnt(6)
	v_pk_mul_f32 v[28:29], v[58:59], v[36:37] op_sel_hi:[1,0]
	v_pk_fma_f32 v[28:29], v[60:61], v[36:37], v[28:29] op_sel:[0,1,0]
	v_pk_fma_f32 v[28:29], v[62:63], v[38:39], v[28:29] op_sel_hi:[1,0,1]
	v_pk_fma_f32 v[28:29], v[64:65], v[38:39], v[28:29] op_sel:[0,1,0]
	v_pk_mul_f32 v[66:67], v[58:59], v[40:41] op_sel_hi:[1,0]
	v_pk_mul_f32 v[68:69], v[60:61], v[40:41] op_sel:[0,1]
	v_add_f32_dpp v28, v28, v28 quad_perm:[1,0,3,2] row_mask:0xf bank_mask:0xf bound_ctrl:1
	v_add_f32_dpp v29, v29, v29 quad_perm:[1,0,3,2] row_mask:0xf bank_mask:0xf bound_ctrl:1
	v_pk_mul_f32 v[70:71], v[62:63], v[42:43] op_sel_hi:[1,0]
	v_add_f32_dpp v28, v28, v28 quad_perm:[2,3,0,1] row_mask:0xf bank_mask:0xf bound_ctrl:1
	v_add_f32_dpp v29, v29, v29 quad_perm:[2,3,0,1] row_mask:0xf bank_mask:0xf bound_ctrl:1
	v_pk_mul_f32 v[72:73], v[64:65], v[42:43] op_sel:[0,1]
	v_add_f32_dpp v28, v28, v28 row_half_mirror row_mask:0xf bank_mask:0xf bound_ctrl:1
	v_add_f32_dpp v29, v29, v29 row_half_mirror row_mask:0xf bank_mask:0xf bound_ctrl:1
	v_pk_fma_f32 v[66:67], v[56:57], v[48:49], v[66:67] op_sel_hi:[1,0,1]
	v_add_f32_dpp v28, v28, v28 row_mirror row_mask:0xf bank_mask:0xf bound_ctrl:1
	v_add_f32_dpp v29, v29, v29 row_mirror row_mask:0xf bank_mask:0xf bound_ctrl:1
	v_pk_fma_f32 v[68:69], v[56:57], v[48:49], v[68:69] op_sel:[0,1,0]
	v_pk_fma_f32 v[70:71], v[56:57], v[50:51], v[70:71] op_sel_hi:[1,0,1]
	v_pk_fma_f32 v[72:73], v[56:57], v[50:51], v[72:73] op_sel:[0,1,0]
	v_pk_fma_f32 v[58:59], v[28:29], v[44:45], v[66:67] op_sel_hi:[1,0,1] neg_lo:[1,0,0] neg_hi:[1,0,0]
	v_pk_fma_f32 v[60:61], v[28:29], v[44:45], v[68:69] op_sel:[0,1,0] neg_lo:[1,0,0] neg_hi:[1,0,0]
	v_pk_fma_f32 v[62:63], v[28:29], v[46:47], v[70:71] op_sel_hi:[1,0,1] neg_lo:[1,0,0] neg_hi:[1,0,0]
	v_pk_fma_f32 v[64:65], v[28:29], v[46:47], v[72:73] op_sel:[0,1,0] neg_lo:[1,0,0] neg_hi:[1,0,0]
	v_pk_mul_f32 v[92:93], v[58:59], v[52:53] op_sel_hi:[1,0]
	v_pk_fma_f32 v[92:93], v[60:61], v[52:53], v[92:93] op_sel:[0,1,0]
	v_pk_fma_f32 v[92:93], v[62:63], v[54:55], v[92:93] op_sel_hi:[1,0,1]
	v_pk_fma_f32 v[92:93], v[64:65], v[54:55], v[92:93] op_sel:[0,1,0]
	ds_read_b128 v[36:39], v3 offset:13312
	ds_read_b128 v[40:43], v3 offset:21504
	ds_read_b64 v[56:57], v34 offset:5120
	ds_read_b128 v[48:51], v3 offset:9216
	ds_read_b128 v[44:47], v3 offset:17408
	ds_read_b128 v[52:55], v3 offset:1024
	s_waitcnt lgkmcnt(6)
; template <int RB, int EK, int D> __device__ __forceinline__ void rwkv_item_ws(const Params& p, int j, int s, int hd, int rq, char* shm_) {
;     ...
;       auto ld = [&](int stp, f32x2* kk_, f32x2* w_, f32x2* b_, f32x2* k2_, f32x2* r_, float* vv_) {
;         int t = d == 0 ? stp : CH - 1 - stp;
;         int o = t * 64 + kq * EK;
; #pragma unroll
;         for (int e = 0; e < NP; ++e) {
;           kk_[e] = *reinterpret_cast<const f32x2*>(skk + o + 2 * e);
;           w_[e] = *reinterpret_cast<const f32x2*>(sw + o + 2 * e);
;           b_[e] = *reinterpret_cast<const f32x2*>(sb + o + 2 * e);
;           k2_[e] = *reinterpret_cast<const f32x2*>(sk + o + 2 * e);
;           r_[e] = *reinterpret_cast<const f32x2*>(sr + o + 2 * e);
;         }
; #pragma unroll
;         for (int rb = 0; rb < RB; ++rb) vv_[rb] = sv[t * 64 + row0 + rb];
;       };
;       ld(0, kkc_, wc_, bc_, k2c_, rc_, vvc);
;       float ys[CH][RB];
; #pragma unroll
;       for (int stp = 0; stp < CH; ++stp) {
;         f32x2 kkn_[NP], wn_[NP], bn_[NP], k2n_[NP], rn_[NP];
;         float vvn[RB];
;         ld(stp < CH - 1 ? stp + 1 : CH - 1, kkn_, wn_, bn_, k2n_, rn_, vvn);
; #pragma unroll
;         for (int rb = 0; rb < RB; ++rb) {
;           f32x2 acc2 = S[rb][0] * kkc_[0] + S[rb][1] * kkc_[1];
;           if constexpr (NP == 4) acc2 += S[rb][2] * kkc_[2] + S[rb][3] * kkc_[3];
;           float sa = reduce_row<LPR>(-(acc2[0] + acc2[1]));
;           f32x2 sa2 = {sa, sa}, vv2 = {vvc[rb], vvc[rb]};
; #pragma unroll
;           for (int e = 0; e < NP; ++e) S[rb][e] = S[rb][e] * wc_[e] + sa2 * bc_[e] + vv2 * k2c_[e];
;           f32x2 y2 = S[rb][0] * rc_[0] + S[rb][1] * rc_[1];
;           if constexpr (NP == 4) y2 += S[rb][2] * rc_[2] + S[rb][3] * rc_[3];
;           ys[stp][rb] = reduce_row<LPR>(y2[0] + y2[1]);
;         }
	v_pk_mul_f32 v[28:29], v[58:59], v[6:7] op_sel_hi:[1,0]
	v_pk_fma_f32 v[28:29], v[60:61], v[6:7], v[28:29] op_sel:[0,1,0]
	v_pk_fma_f32 v[28:29], v[62:63], v[8:9], v[28:29] op_sel_hi:[1,0,1]
	v_pk_fma_f32 v[28:29], v[64:65], v[8:9], v[28:29] op_sel:[0,1,0]
	v_pk_mul_f32 v[66:67], v[58:59], v[10:11] op_sel_hi:[1,0]
	v_pk_mul_f32 v[68:69], v[60:61], v[10:11] op_sel:[0,1]
	v_add_f32_dpp v28, v28, v28 quad_perm:[1,0,3,2] row_mask:0xf bank_mask:0xf bound_ctrl:1
	v_add_f32_dpp v29, v29, v29 quad_perm:[1,0,3,2] row_mask:0xf bank_mask:0xf bound_ctrl:1
	v_pk_mul_f32 v[70:71], v[62:63], v[12:13] op_sel_hi:[1,0]
	v_add_f32_dpp v28, v28, v28 quad_perm:[2,3,0,1] row_mask:0xf bank_mask:0xf bound_ctrl:1
	v_add_f32_dpp v29, v29, v29 quad_perm:[2,3,0,1] row_mask:0xf bank_mask:0xf bound_ctrl:1
	v_pk_mul_f32 v[72:73], v[64:65], v[12:13] op_sel:[0,1]
	v_add_f32_dpp v28, v28, v28 row_half_mirror row_mask:0xf bank_mask:0xf bound_ctrl:1
	v_add_f32_dpp v29, v29, v29 row_half_mirror row_mask:0xf bank_mask:0xf bound_ctrl:1
	v_pk_fma_f32 v[66:67], v[26:27], v[18:19], v[66:67] op_sel_hi:[1,0,1]
	v_add_f32_dpp v28, v28, v28 row_mirror row_mask:0xf bank_mask:0xf bound_ctrl:1
	v_add_f32_dpp v29, v29, v29 row_mirror row_mask:0xf bank_mask:0xf bound_ctrl:1
	v_pk_fma_f32 v[68:69], v[26:27], v[18:19], v[68:69] op_sel:[0,1,0]
	v_pk_fma_f32 v[70:71], v[26:27], v[20:21], v[70:71] op_sel_hi:[1,0,1]
	v_pk_fma_f32 v[72:73], v[26:27], v[20:21], v[72:73] op_sel:[0,1,0]
	v_pk_fma_f32 v[58:59], v[28:29], v[14:15], v[66:67] op_sel_hi:[1,0,1] neg_lo:[1,0,0] neg_hi:[1,0,0]
	v_pk_fma_f32 v[60:61], v[28:29], v[14:15], v[68:69] op_sel:[0,1,0] neg_lo:[1,0,0] neg_hi:[1,0,0]
	v_pk_fma_f32 v[62:63], v[28:29], v[16:17], v[70:71] op_sel_hi:[1,0,1] neg_lo:[1,0,0] neg_hi:[1,0,0]
	v_pk_fma_f32 v[64:65], v[28:29], v[16:17], v[72:73] op_sel:[0,1,0] neg_lo:[1,0,0] neg_hi:[1,0,0]
	v_pk_mul_f32 v[94:95], v[58:59], v[22:23] op_sel_hi:[1,0]
	v_pk_fma_f32 v[94:95], v[60:61], v[22:23], v[94:95] op_sel:[0,1,0]
	v_pk_fma_f32 v[94:95], v[62:63], v[24:25], v[94:95] op_sel_hi:[1,0,1]
	v_pk_fma_f32 v[94:95], v[64:65], v[24:25], v[94:95] op_sel:[0,1,0]
	ds_read_b128 v[6:9], v3 offset:13056
	ds_read_b128 v[10:13], v3 offset:21248
	ds_read_b64 v[26:27], v34 offset:4864
	ds_read_b128 v[18:21], v3 offset:8960
	ds_read_b128 v[14:17], v3 offset:17152
	ds_read_b128 v[22:25], v3 offset:768
	s_waitcnt lgkmcnt(6)
	v_pk_mul_f32 v[28:29], v[58:59], v[36:37] op_sel_hi:[1,0]
	v_pk_fma_f32 v[28:29], v[60:61], v[36:37], v[28:29] op_sel:[0,1,0]
	v_pk_fma_f32 v[28:29], v[62:63], v[38:39], v[28:29] op_sel_hi:[1,0,1]
	v_pk_fma_f32 v[28:29], v[64:65], v[38:39], v[28:29] op_sel:[0,1,0]
	v_pk_mul_f32 v[66:67], v[58:59], v[40:41] op_sel_hi:[1,0]
	v_pk_mul_f32 v[68:69], v[60:61], v[40:41] op_sel:[0,1]
	v_add_f32_dpp v28, v28, v28 quad_perm:[1,0,3,2] row_mask:0xf bank_mask:0xf bound_ctrl:1
	v_add_f32_dpp v29, v29, v29 quad_perm:[1,0,3,2] row_mask:0xf bank_mask:0xf bound_ctrl:1
	v_pk_mul_f32 v[70:71], v[62:63], v[42:43] op_sel_hi:[1,0]
	v_add_f32_dpp v28, v28, v28 quad_perm:[2,3,0,1] row_mask:0xf bank_mask:0xf bound_ctrl:1
	v_add_f32_dpp v29, v29, v29 quad_perm:[2,3,0,1] row_mask:0xf bank_mask:0xf bound_ctrl:1
	v_pk_mul_f32 v[72:73], v[64:65], v[42:43] op_sel:[0,1]
	v_add_f32_dpp v28, v28, v28 row_half_mirror row_mask:0xf bank_mask:0xf bound_ctrl:1
	v_add_f32_dpp v29, v29, v29 row_half_mirror row_mask:0xf bank_mask:0xf bound_ctrl:1
	v_pk_fma_f32 v[66:67], v[56:57], v[48:49], v[66:67] op_sel_hi:[1,0,1]
	v_add_f32_dpp v28, v28, v28 row_mirror row_mask:0xf bank_mask:0xf bound_ctrl:1
	v_add_f32_dpp v29, v29, v29 row_mirror row_mask:0xf bank_mask:0xf bound_ctrl:1
	v_pk_fma_f32 v[68:69], v[56:57], v[48:49], v[68:69] op_sel:[0,1,0]
	v_pk_fma_f32 v[70:71], v[56:57], v[50:51], v[70:71] op_sel_hi:[1,0,1]
	v_pk_fma_f32 v[72:73], v[56:57], v[50:51], v[72:73] op_sel:[0,1,0]
	v_pk_fma_f32 v[58:59], v[28:29], v[44:45], v[66:67] op_sel_hi:[1,0,1] neg_lo:[1,0,0] neg_hi:[1,0,0]
	v_pk_fma_f32 v[60:61], v[28:29], v[44:45], v[68:69] op_sel:[0,1,0] neg_lo:[1,0,0] neg_hi:[1,0,0]
	v_pk_fma_f32 v[62:63], v[28:29], v[46:47], v[70:71] op_sel_hi:[1,0,1] neg_lo:[1,0,0] neg_hi:[1,0,0]
	v_pk_fma_f32 v[64:65], v[28:29], v[46:47], v[72:73] op_sel:[0,1,0] neg_lo:[1,0,0] neg_hi:[1,0,0]
	v_pk_mul_f32 v[96:97], v[58:59], v[52:53] op_sel_hi:[1,0]
	v_pk_fma_f32 v[96:97], v[60:61], v[52:53], v[96:97] op_sel:[0,1,0]
	v_pk_fma_f32 v[96:97], v[62:63], v[54:55], v[96:97] op_sel_hi:[1,0,1]
	v_pk_fma_f32 v[96:97], v[64:65], v[54:55], v[96:97] op_sel:[0,1,0]
	ds_read_b128 v[36:39], v3 offset:12800
	ds_read_b128 v[40:43], v3 offset:20992
	ds_read_b64 v[56:57], v34 offset:4608
	ds_read_b128 v[48:51], v3 offset:8704
	ds_read_b128 v[44:47], v3 offset:16896
	ds_read_b128 v[52:55], v3 offset:512
	s_waitcnt lgkmcnt(6)
; template <int RB, int EK, int D> __device__ __forceinline__ void rwkv_item_ws(const Params& p, int j, int s, int hd, int rq, char* shm_) {
;     ...
;       auto ld = [&](int stp, f32x2* kk_, f32x2* w_, f32x2* b_, f32x2* k2_, f32x2* r_, float* vv_) {
;         int t = d == 0 ? stp : CH - 1 - stp;
;         int o = t * 64 + kq * EK;
; #pragma unroll
;         for (int e = 0; e < NP; ++e) {
;           kk_[e] = *reinterpret_cast<const f32x2*>(skk + o + 2 * e);
;           w_[e] = *reinterpret_cast<const f32x2*>(sw + o + 2 * e);
;           b_[e] = *reinterpret_cast<const f32x2*>(sb + o + 2 * e);
;           k2_[e] = *reinterpret_cast<const f32x2*>(sk + o + 2 * e);
;           r_[e] = *reinterpret_cast<const f32x2*>(sr + o + 2 * e);
;         }
; #pragma unroll
;         for (int rb = 0; rb < RB; ++rb) vv_[rb] = sv[t * 64 + row0 + rb];
;       };
;       ld(0, kkc_, wc_, bc_, k2c_, rc_, vvc);
;       float ys[CH][RB];
; #pragma unroll
;       for (int stp = 0; stp < CH; ++stp) {
;         f32x2 kkn_[NP], wn_[NP], bn_[NP], k2n_[NP], rn_[NP];
;         float vvn[RB];
;         ld(stp < CH - 1 ? stp + 1 : CH - 1, kkn_, wn_, bn_, k2n_, rn_, vvn);
; #pragma unroll
;         for (int rb = 0; rb < RB; ++rb) {
;           f32x2 acc2 = S[rb][0] * kkc_[0] + S[rb][1] * kkc_[1];
;           if constexpr (NP == 4) acc2 += S[rb][2] * kkc_[2] + S[rb][3] * kkc_[3];
;           float sa = reduce_row<LPR>(-(acc2[0] + acc2[1]));
;           f32x2 sa2 = {sa, sa}, vv2 = {vvc[rb], vvc[rb]};
; #pragma unroll
;           for (int e = 0; e < NP; ++e) S[rb][e] = S[rb][e] * wc_[e] + sa2 * bc_[e] + vv2 * k2c_[e];
;           f32x2 y2 = S[rb][0] * rc_[0] + S[rb][1] * rc_[1];
;           if constexpr (NP == 4) y2 += S[rb][2] * rc_[2] + S[rb][3] * rc_[3];
;           ys[stp][rb] = reduce_row<LPR>(y2[0] + y2[1]);
;         }
	v_pk_mul_f32 v[28:29], v[58:59], v[6:7] op_sel_hi:[1,0]
	v_pk_fma_f32 v[28:29], v[60:61], v[6:7], v[28:29] op_sel:[0,1,0]
	v_pk_fma_f32 v[28:29], v[62:63], v[8:9], v[28:29] op_sel_hi:[1,0,1]
	v_pk_fma_f32 v[28:29], v[64:65], v[8:9], v[28:29] op_sel:[0,1,0]
	v_pk_mul_f32 v[66:67], v[58:59], v[10:11] op_sel_hi:[1,0]
	v_pk_mul_f32 v[68:69], v[60:61], v[10:11] op_sel:[0,1]
	v_add_f32_dpp v28, v28, v28 quad_perm:[1,0,3,2] row_mask:0xf bank_mask:0xf bound_ctrl:1
	v_add_f32_dpp v29, v29, v29 quad_perm:[1,0,3,2] row_mask:0xf bank_mask:0xf bound_ctrl:1
	v_pk_mul_f32 v[70:71], v[62:63], v[12:13] op_sel_hi:[1,0]
	v_add_f32_dpp v28, v28, v28 quad_perm:[2,3,0,1] row_mask:0xf bank_mask:0xf bound_ctrl:1
	v_add_f32_dpp v29, v29, v29 quad_perm:[2,3,0,1] row_mask:0xf bank_mask:0xf bound_ctrl:1
	v_pk_mul_f32 v[72:73], v[64:65], v[12:13] op_sel:[0,1]
	v_add_f32_dpp v28, v28, v28 row_half_mirror row_mask:0xf bank_mask:0xf bound_ctrl:1
	v_add_f32_dpp v29, v29, v29 row_half_mirror row_mask:0xf bank_mask:0xf bound_ctrl:1
	v_pk_fma_f32 v[66:67], v[26:27], v[18:19], v[66:67] op_sel_hi:[1,0,1]
	v_add_f32_dpp v28, v28, v28 row_mirror row_mask:0xf bank_mask:0xf bound_ctrl:1
	v_add_f32_dpp v29, v29, v29 row_mirror row_mask:0xf bank_mask:0xf bound_ctrl:1
	v_pk_fma_f32 v[68:69], v[26:27], v[18:19], v[68:69] op_sel:[0,1,0]
	v_pk_fma_f32 v[70:71], v[26:27], v[20:21], v[70:71] op_sel_hi:[1,0,1]
	v_pk_fma_f32 v[72:73], v[26:27], v[20:21], v[72:73] op_sel:[0,1,0]
	v_pk_fma_f32 v[58:59], v[28:29], v[14:15], v[66:67] op_sel_hi:[1,0,1] neg_lo:[1,0,0] neg_hi:[1,0,0]
	v_pk_fma_f32 v[60:61], v[28:29], v[14:15], v[68:69] op_sel:[0,1,0] neg_lo:[1,0,0] neg_hi:[1,0,0]
	v_pk_fma_f32 v[62:63], v[28:29], v[16:17], v[70:71] op_sel_hi:[1,0,1] neg_lo:[1,0,0] neg_hi:[1,0,0]
	v_pk_fma_f32 v[64:65], v[28:29], v[16:17], v[72:73] op_sel:[0,1,0] neg_lo:[1,0,0] neg_hi:[1,0,0]
	v_pk_mul_f32 v[98:99], v[58:59], v[22:23] op_sel_hi:[1,0]
	v_pk_fma_f32 v[98:99], v[60:61], v[22:23], v[98:99] op_sel:[0,1,0]
	v_pk_fma_f32 v[98:99], v[62:63], v[24:25], v[98:99] op_sel_hi:[1,0,1]
	v_pk_fma_f32 v[98:99], v[64:65], v[24:25], v[98:99] op_sel:[0,1,0]
	ds_read_b128 v[6:9], v3 offset:12544
	ds_read_b128 v[10:13], v3 offset:20736
	ds_read_b64 v[26:27], v34 offset:4352
	ds_read_b128 v[18:21], v3 offset:8448
	ds_read_b128 v[14:17], v3 offset:16640
	ds_read_b128 v[22:25], v3 offset:256
	s_waitcnt lgkmcnt(6)
	v_pk_mul_f32 v[28:29], v[58:59], v[36:37] op_sel_hi:[1,0]
	v_pk_fma_f32 v[28:29], v[60:61], v[36:37], v[28:29] op_sel:[0,1,0]
	v_pk_fma_f32 v[28:29], v[62:63], v[38:39], v[28:29] op_sel_hi:[1,0,1]
	v_pk_fma_f32 v[28:29], v[64:65], v[38:39], v[28:29] op_sel:[0,1,0]
	v_pk_mul_f32 v[66:67], v[58:59], v[40:41] op_sel_hi:[1,0]
	v_pk_mul_f32 v[68:69], v[60:61], v[40:41] op_sel:[0,1]
	v_add_f32_dpp v28, v28, v28 quad_perm:[1,0,3,2] row_mask:0xf bank_mask:0xf bound_ctrl:1
	v_add_f32_dpp v29, v29, v29 quad_perm:[1,0,3,2] row_mask:0xf bank_mask:0xf bound_ctrl:1
	v_pk_mul_f32 v[70:71], v[62:63], v[42:43] op_sel_hi:[1,0]
	v_add_f32_dpp v28, v28, v28 quad_perm:[2,3,0,1] row_mask:0xf bank_mask:0xf bound_ctrl:1
	v_add_f32_dpp v29, v29, v29 quad_perm:[2,3,0,1] row_mask:0xf bank_mask:0xf bound_ctrl:1
	v_pk_mul_f32 v[72:73], v[64:65], v[42:43] op_sel:[0,1]
	v_add_f32_dpp v28, v28, v28 row_half_mirror row_mask:0xf bank_mask:0xf bound_ctrl:1
	v_add_f32_dpp v29, v29, v29 row_half_mirror row_mask:0xf bank_mask:0xf bound_ctrl:1
	v_pk_fma_f32 v[66:67], v[56:57], v[48:49], v[66:67] op_sel_hi:[1,0,1]
	v_add_f32_dpp v28, v28, v28 row_mirror row_mask:0xf bank_mask:0xf bound_ctrl:1
	v_add_f32_dpp v29, v29, v29 row_mirror row_mask:0xf bank_mask:0xf bound_ctrl:1
	v_pk_fma_f32 v[68:69], v[56:57], v[48:49], v[68:69] op_sel:[0,1,0]
	v_pk_fma_f32 v[70:71], v[56:57], v[50:51], v[70:71] op_sel_hi:[1,0,1]
	v_pk_fma_f32 v[72:73], v[56:57], v[50:51], v[72:73] op_sel:[0,1,0]
	v_pk_fma_f32 v[58:59], v[28:29], v[44:45], v[66:67] op_sel_hi:[1,0,1] neg_lo:[1,0,0] neg_hi:[1,0,0]
	v_pk_fma_f32 v[60:61], v[28:29], v[44:45], v[68:69] op_sel:[0,1,0] neg_lo:[1,0,0] neg_hi:[1,0,0]
	v_pk_fma_f32 v[62:63], v[28:29], v[46:47], v[70:71] op_sel_hi:[1,0,1] neg_lo:[1,0,0] neg_hi:[1,0,0]
	v_pk_fma_f32 v[64:65], v[28:29], v[46:47], v[72:73] op_sel:[0,1,0] neg_lo:[1,0,0] neg_hi:[1,0,0]
	v_pk_mul_f32 v[100:101], v[58:59], v[52:53] op_sel_hi:[1,0]
	v_pk_fma_f32 v[100:101], v[60:61], v[52:53], v[100:101] op_sel:[0,1,0]
	v_pk_fma_f32 v[100:101], v[62:63], v[54:55], v[100:101] op_sel_hi:[1,0,1]
	v_pk_fma_f32 v[100:101], v[64:65], v[54:55], v[100:101] op_sel:[0,1,0]
	ds_read_b128 v[36:39], v3 offset:12288
	ds_read_b128 v[40:43], v3 offset:20480
	ds_read_b64 v[56:57], v34 offset:4096
	ds_read_b128 v[48:51], v3 offset:8192
	ds_read_b128 v[44:47], v3 offset:16384
	ds_read_b128 v[52:55], v3 offset:0
	s_waitcnt lgkmcnt(6)
; template <int RB, int EK, int D> __device__ __forceinline__ void rwkv_item_ws(const Params& p, int j, int s, int hd, int rq, char* shm_) {
;     ...
;       for (int stp = 0; stp < CH; ++stp) {
;         f32x2 kkn_[NP], wn_[NP], bn_[NP], k2n_[NP], rn_[NP];
;         float vvn[RB];
;         ld(stp < CH - 1 ? stp + 1 : CH - 1, kkn_, wn_, bn_, k2n_, rn_, vvn);
; #pragma unroll
;         for (int rb = 0; rb < RB; ++rb) {
;           f32x2 acc2 = S[rb][0] * kkc_[0] + S[rb][1] * kkc_[1];
;           if constexpr (NP == 4) acc2 += S[rb][2] * kkc_[2] + S[rb][3] * kkc_[3];
;           float sa = reduce_row<LPR>(-(acc2[0] + acc2[1]));
;           f32x2 sa2 = {sa, sa}, vv2 = {vvc[rb], vvc[rb]};
; #pragma unroll
;           for (int e = 0; e < NP; ++e) S[rb][e] = S[rb][e] * wc_[e] + sa2 * bc_[e] + vv2 * k2c_[e];
;           f32x2 y2 = S[rb][0] * rc_[0] + S[rb][1] * rc_[1];
;           if constexpr (NP == 4) y2 += S[rb][2] * rc_[2] + S[rb][3] * rc_[3];
;           ys[stp][rb] = reduce_row<LPR>(y2[0] + y2[1]);
	v_pk_mul_f32 v[28:29], v[58:59], v[6:7] op_sel_hi:[1,0]
	v_pk_fma_f32 v[28:29], v[60:61], v[6:7], v[28:29] op_sel:[0,1,0]
	v_pk_fma_f32 v[28:29], v[62:63], v[8:9], v[28:29] op_sel_hi:[1,0,1]
	v_pk_fma_f32 v[28:29], v[64:65], v[8:9], v[28:29] op_sel:[0,1,0]
	v_pk_mul_f32 v[66:67], v[58:59], v[10:11] op_sel_hi:[1,0]
	v_pk_mul_f32 v[68:69], v[60:61], v[10:11] op_sel:[0,1]
	v_add_f32_dpp v28, v28, v28 quad_perm:[1,0,3,2] row_mask:0xf bank_mask:0xf bound_ctrl:1
	v_add_f32_dpp v29, v29, v29 quad_perm:[1,0,3,2] row_mask:0xf bank_mask:0xf bound_ctrl:1
	v_pk_mul_f32 v[70:71], v[62:63], v[12:13] op_sel_hi:[1,0]
	v_add_f32_dpp v28, v28, v28 quad_perm:[2,3,0,1] row_mask:0xf bank_mask:0xf bound_ctrl:1
	v_add_f32_dpp v29, v29, v29 quad_perm:[2,3,0,1] row_mask:0xf bank_mask:0xf bound_ctrl:1
	v_pk_mul_f32 v[72:73], v[64:65], v[12:13] op_sel:[0,1]
	v_add_f32_dpp v28, v28, v28 row_half_mirror row_mask:0xf bank_mask:0xf bound_ctrl:1
	v_add_f32_dpp v29, v29, v29 row_half_mirror row_mask:0xf bank_mask:0xf bound_ctrl:1
	v_pk_fma_f32 v[66:67], v[26:27], v[18:19], v[66:67] op_sel_hi:[1,0,1]
	v_add_f32_dpp v28, v28, v28 row_mirror row_mask:0xf bank_mask:0xf bound_ctrl:1
	v_add_f32_dpp v29, v29, v29 row_mirror row_mask:0xf bank_mask:0xf bound_ctrl:1
	v_pk_fma_f32 v[68:69], v[26:27], v[18:19], v[68:69] op_sel:[0,1,0]
	v_pk_fma_f32 v[70:71], v[26:27], v[20:21], v[70:71] op_sel_hi:[1,0,1]
	v_pk_fma_f32 v[72:73], v[26:27], v[20:21], v[72:73] op_sel:[0,1,0]
	v_pk_fma_f32 v[58:59], v[28:29], v[14:15], v[66:67] op_sel_hi:[1,0,1] neg_lo:[1,0,0] neg_hi:[1,0,0]
	v_pk_fma_f32 v[60:61], v[28:29], v[14:15], v[68:69] op_sel:[0,1,0] neg_lo:[1,0,0] neg_hi:[1,0,0]
	v_pk_fma_f32 v[62:63], v[28:29], v[16:17], v[70:71] op_sel_hi:[1,0,1] neg_lo:[1,0,0] neg_hi:[1,0,0]
	v_pk_fma_f32 v[64:65], v[28:29], v[16:17], v[72:73] op_sel:[0,1,0] neg_lo:[1,0,0] neg_hi:[1,0,0]
	v_pk_mul_f32 v[102:103], v[58:59], v[22:23] op_sel_hi:[1,0]
	v_pk_fma_f32 v[102:103], v[60:61], v[22:23], v[102:103] op_sel:[0,1,0]
	v_pk_fma_f32 v[102:103], v[62:63], v[24:25], v[102:103] op_sel_hi:[1,0,1]
	v_pk_fma_f32 v[102:103], v[64:65], v[24:25], v[102:103] op_sel:[0,1,0]
	s_waitcnt lgkmcnt(0)
	v_pk_mul_f32 v[28:29], v[58:59], v[36:37] op_sel_hi:[1,0]
	v_pk_fma_f32 v[28:29], v[60:61], v[36:37], v[28:29] op_sel:[0,1,0]
	v_pk_fma_f32 v[28:29], v[62:63], v[38:39], v[28:29] op_sel_hi:[1,0,1]
	v_pk_fma_f32 v[28:29], v[64:65], v[38:39], v[28:29] op_sel:[0,1,0]
	v_pk_mul_f32 v[66:67], v[58:59], v[40:41] op_sel_hi:[1,0]
	v_pk_mul_f32 v[68:69], v[60:61], v[40:41] op_sel:[0,1]
	v_add_f32_dpp v28, v28, v28 quad_perm:[1,0,3,2] row_mask:0xf bank_mask:0xf bound_ctrl:1
	v_add_f32_dpp v29, v29, v29 quad_perm:[1,0,3,2] row_mask:0xf bank_mask:0xf bound_ctrl:1
	v_pk_mul_f32 v[70:71], v[62:63], v[42:43] op_sel_hi:[1,0]
	v_add_f32_dpp v28, v28, v28 quad_perm:[2,3,0,1] row_mask:0xf bank_mask:0xf bound_ctrl:1
	v_add_f32_dpp v29, v29, v29 quad_perm:[2,3,0,1] row_mask:0xf bank_mask:0xf bound_ctrl:1
	v_pk_mul_f32 v[72:73], v[64:65], v[42:43] op_sel:[0,1]
	v_add_f32_dpp v28, v28, v28 row_half_mirror row_mask:0xf bank_mask:0xf bound_ctrl:1
	v_add_f32_dpp v29, v29, v29 row_half_mirror row_mask:0xf bank_mask:0xf bound_ctrl:1
	v_pk_fma_f32 v[66:67], v[56:57], v[48:49], v[66:67] op_sel_hi:[1,0,1]
	v_add_f32_dpp v28, v28, v28 row_mirror row_mask:0xf bank_mask:0xf bound_ctrl:1
	v_add_f32_dpp v29, v29, v29 row_mirror row_mask:0xf bank_mask:0xf bound_ctrl:1
	v_pk_fma_f32 v[68:69], v[56:57], v[48:49], v[68:69] op_sel:[0,1,0]
	v_pk_fma_f32 v[70:71], v[56:57], v[50:51], v[70:71] op_sel_hi:[1,0,1]
	v_pk_fma_f32 v[72:73], v[56:57], v[50:51], v[72:73] op_sel:[0,1,0]
	v_pk_fma_f32 v[58:59], v[28:29], v[44:45], v[66:67] op_sel_hi:[1,0,1] neg_lo:[1,0,0] neg_hi:[1,0,0]
	v_pk_fma_f32 v[60:61], v[28:29], v[44:45], v[68:69] op_sel:[0,1,0] neg_lo:[1,0,0] neg_hi:[1,0,0]
	v_pk_fma_f32 v[62:63], v[28:29], v[46:47], v[70:71] op_sel_hi:[1,0,1] neg_lo:[1,0,0] neg_hi:[1,0,0]
	v_pk_fma_f32 v[64:65], v[28:29], v[46:47], v[72:73] op_sel:[0,1,0] neg_lo:[1,0,0] neg_hi:[1,0,0]
	v_pk_mul_f32 v[104:105], v[58:59], v[52:53] op_sel_hi:[1,0]
	v_pk_fma_f32 v[104:105], v[60:61], v[52:53], v[104:105] op_sel:[0,1,0]
	v_pk_fma_f32 v[104:105], v[62:63], v[54:55], v[104:105] op_sel_hi:[1,0,1]
	v_pk_fma_f32 v[104:105], v[64:65], v[54:55], v[104:105] op_sel:[0,1,0]
	v_add_f32_dpp v74, v74, v74 row_half_mirror row_mask:0xf bank_mask:0x5 bound_ctrl:1
	v_add_f32_dpp v76, v76, v76 row_half_mirror row_mask:0xf bank_mask:0x5 bound_ctrl:1
	v_add_f32_dpp v74, v75, v75 row_half_mirror row_mask:0xf bank_mask:0xa bound_ctrl:1
	v_add_f32_dpp v76, v77, v77 row_half_mirror row_mask:0xf bank_mask:0xa bound_ctrl:1
	v_add_f32_dpp v78, v78, v78 row_half_mirror row_mask:0xf bank_mask:0x5 bound_ctrl:1
	v_add_f32_dpp v80, v80, v80 row_half_mirror row_mask:0xf bank_mask:0x5 bound_ctrl:1
	v_add_f32_dpp v78, v79, v79 row_half_mirror row_mask:0xf bank_mask:0xa bound_ctrl:1
	v_add_f32_dpp v80, v81, v81 row_half_mirror row_mask:0xf bank_mask:0xa bound_ctrl:1
	v_add_f32_dpp v82, v82, v82 row_half_mirror row_mask:0xf bank_mask:0x5 bound_ctrl:1
	v_add_f32_dpp v84, v84, v84 row_half_mirror row_mask:0xf bank_mask:0x5 bound_ctrl:1
	v_add_f32_dpp v82, v83, v83 row_half_mirror row_mask:0xf bank_mask:0xa bound_ctrl:1
	v_add_f32_dpp v84, v85, v85 row_half_mirror row_mask:0xf bank_mask:0xa bound_ctrl:1
	v_add_f32_dpp v86, v86, v86 row_half_mirror row_mask:0xf bank_mask:0x5 bound_ctrl:1
	v_add_f32_dpp v88, v88, v88 row_half_mirror row_mask:0xf bank_mask:0x5 bound_ctrl:1
	v_add_f32_dpp v86, v87, v87 row_half_mirror row_mask:0xf bank_mask:0xa bound_ctrl:1
; template <int RB, int EK, int D> __device__ __forceinline__ void rwkv_item_ws(const Params& p, int j, int s, int hd, int rq, char* shm_) {
;     ...
;           ys[stp][rb] = reduce_row<LPR>(y2[0] + y2[1]);
;         }
; #pragma unroll
;         for (int e = 0; e < NP; ++e) { kkc_[e] = kkn_[e]; wc_[e] = wn_[e]; bc_[e] = bn_[e]; k2c_[e] = k2n_[e]; rc_[e] = rn_[e]; }
; #pragma unroll
;         for (int rb = 0; rb < RB; ++rb) vvc[rb] = vvn[rb];
;       }
;       if (kq == 0) {
; #pragma unroll
;         for (int stp = 0; stp < CH; ++stp) {
;           int t = d == 0 ? stp : CH - 1 - stp;
;           h16* yp = Y + (size_t)(st + chunk * CH + t) * 512 + hd * 64 + row0;
; #pragma unroll
;           for (int rb = 0; rb < RB; ++rb) yp[rb] = (h16)ys[stp][rb];
;         }
	v_add_f32_dpp v88, v89, v89 row_half_mirror row_mask:0xf bank_mask:0xa bound_ctrl:1
	v_add_f32_dpp v90, v90, v90 row_half_mirror row_mask:0xf bank_mask:0x5 bound_ctrl:1
	v_add_f32_dpp v92, v92, v92 row_half_mirror row_mask:0xf bank_mask:0x5 bound_ctrl:1
	v_add_f32_dpp v90, v91, v91 row_half_mirror row_mask:0xf bank_mask:0xa bound_ctrl:1
	v_add_f32_dpp v92, v93, v93 row_half_mirror row_mask:0xf bank_mask:0xa bound_ctrl:1
	v_add_f32_dpp v94, v94, v94 row_half_mirror row_mask:0xf bank_mask:0x5 bound_ctrl:1
	v_add_f32_dpp v96, v96, v96 row_half_mirror row_mask:0xf bank_mask:0x5 bound_ctrl:1
	v_add_f32_dpp v94, v95, v95 row_half_mirror row_mask:0xf bank_mask:0xa bound_ctrl:1
	v_add_f32_dpp v96, v97, v97 row_half_mirror row_mask:0xf bank_mask:0xa bound_ctrl:1
	v_add_f32_dpp v98, v98, v98 row_half_mirror row_mask:0xf bank_mask:0x5 bound_ctrl:1
	v_add_f32_dpp v100, v100, v100 row_half_mirror row_mask:0xf bank_mask:0x5 bound_ctrl:1
	v_add_f32_dpp v98, v99, v99 row_half_mirror row_mask:0xf bank_mask:0xa bound_ctrl:1
	v_add_f32_dpp v100, v101, v101 row_half_mirror row_mask:0xf bank_mask:0xa bound_ctrl:1
	v_add_f32_dpp v102, v102, v102 row_half_mirror row_mask:0xf bank_mask:0x5 bound_ctrl:1
	v_add_f32_dpp v104, v104, v104 row_half_mirror row_mask:0xf bank_mask:0x5 bound_ctrl:1
	v_add_f32_dpp v102, v103, v103 row_half_mirror row_mask:0xf bank_mask:0xa bound_ctrl:1
	v_add_f32_dpp v104, v105, v105 row_half_mirror row_mask:0xf bank_mask:0xa bound_ctrl:1
	v_add_f32_dpp v74, v74, v74 row_ror:8 row_mask:0xf bank_mask:0x3 bound_ctrl:1
	v_add_f32_dpp v78, v78, v78 row_ror:8 row_mask:0xf bank_mask:0x3 bound_ctrl:1
	v_add_f32_dpp v74, v76, v76 row_ror:8 row_mask:0xf bank_mask:0xc bound_ctrl:1
	v_add_f32_dpp v78, v80, v80 row_ror:8 row_mask:0xf bank_mask:0xc bound_ctrl:1
	v_add_f32_dpp v82, v82, v82 row_ror:8 row_mask:0xf bank_mask:0x3 bound_ctrl:1
	v_add_f32_dpp v86, v86, v86 row_ror:8 row_mask:0xf bank_mask:0x3 bound_ctrl:1
	v_add_f32_dpp v82, v84, v84 row_ror:8 row_mask:0xf bank_mask:0xc bound_ctrl:1
	v_add_f32_dpp v86, v88, v88 row_ror:8 row_mask:0xf bank_mask:0xc bound_ctrl:1
	v_add_f32_dpp v90, v90, v90 row_ror:8 row_mask:0xf bank_mask:0x3 bound_ctrl:1
	v_add_f32_dpp v94, v94, v94 row_ror:8 row_mask:0xf bank_mask:0x3 bound_ctrl:1
	v_add_f32_dpp v90, v92, v92 row_ror:8 row_mask:0xf bank_mask:0xc bound_ctrl:1
	v_add_f32_dpp v94, v96, v96 row_ror:8 row_mask:0xf bank_mask:0xc bound_ctrl:1
	v_add_f32_dpp v98, v98, v98 row_ror:8 row_mask:0xf bank_mask:0x3 bound_ctrl:1
	v_add_f32_dpp v102, v102, v102 row_ror:8 row_mask:0xf bank_mask:0x3 bound_ctrl:1
	v_add_f32_dpp v98, v100, v100 row_ror:8 row_mask:0xf bank_mask:0xc bound_ctrl:1
	v_add_f32_dpp v102, v104, v104 row_ror:8 row_mask:0xf bank_mask:0xc bound_ctrl:1
	v_add_f32_dpp v74, v74, v74 quad_perm:[1,0,3,2] row_mask:0xf bank_mask:0xf bound_ctrl:1
	v_add_f32_dpp v78, v78, v78 quad_perm:[1,0,3,2] row_mask:0xf bank_mask:0xf bound_ctrl:1
	v_add_f32_dpp v82, v82, v82 quad_perm:[1,0,3,2] row_mask:0xf bank_mask:0xf bound_ctrl:1
	v_add_f32_dpp v86, v86, v86 quad_perm:[1,0,3,2] row_mask:0xf bank_mask:0xf bound_ctrl:1
	v_add_f32_dpp v90, v90, v90 quad_perm:[1,0,3,2] row_mask:0xf bank_mask:0xf bound_ctrl:1
	v_add_f32_dpp v94, v94, v94 quad_perm:[1,0,3,2] row_mask:0xf bank_mask:0xf bound_ctrl:1
	v_add_f32_dpp v98, v98, v98 quad_perm:[1,0,3,2] row_mask:0xf bank_mask:0xf bound_ctrl:1
	v_add_f32_dpp v102, v102, v102 quad_perm:[1,0,3,2] row_mask:0xf bank_mask:0xf bound_ctrl:1
	v_add_f32_dpp v74, v74, v74 quad_perm:[2,3,0,1] row_mask:0xf bank_mask:0xf bound_ctrl:1
	v_add_f32_dpp v78, v78, v78 quad_perm:[2,3,0,1] row_mask:0xf bank_mask:0xf bound_ctrl:1
	v_add_f32_dpp v82, v82, v82 quad_perm:[2,3,0,1] row_mask:0xf bank_mask:0xf bound_ctrl:1
	v_add_f32_dpp v86, v86, v86 quad_perm:[2,3,0,1] row_mask:0xf bank_mask:0xf bound_ctrl:1
	v_add_f32_dpp v90, v90, v90 quad_perm:[2,3,0,1] row_mask:0xf bank_mask:0xf bound_ctrl:1
	v_add_f32_dpp v94, v94, v94 quad_perm:[2,3,0,1] row_mask:0xf bank_mask:0xf bound_ctrl:1
	v_add_f32_dpp v98, v98, v98 quad_perm:[2,3,0,1] row_mask:0xf bank_mask:0xf bound_ctrl:1
	v_add_f32_dpp v102, v102, v102 quad_perm:[2,3,0,1] row_mask:0xf bank_mask:0xf bound_ctrl:1
	v_and_b32_e32 v113, 12, v0
	v_cmp_eq_u32_e32 vcc, 0, v113
	v_lshrrev_b32_e32 v114, 4, v0
	v_and_b32_e32 v115, 1, v114
	v_lshlrev_b32_e32 v115, 1, v115
	v_lshrrev_b32_e32 v114, 1, v114
	v_mul_i32_i24_e32 v114, -1024, v114
	v_add_u32_e32 v114, v114, v115
	v_ashrrev_i32_e32 v115, 31, v114
	s_and_saveexec_b64 s[12:13], vcc
	s_cbranch_execz .LBB0_2081
	s_add_i32 s16, s6, 4
	s_ashr_i32 s17, s16, 31
	s_lshl_b64 s[16:17], s[16:17], 10
	v_lshl_add_u64 v[106:107], v[4:5], 0, s[16:17]
	v_lshl_add_u64 v[106:107], v[106:107], 0, v[114:115]
	s_add_i32 s16, s6, 12
	s_ashr_i32 s17, s16, 31
	s_lshl_b64 s[16:17], s[16:17], 10
	v_lshl_add_u64 v[108:109], v[4:5], 0, s[16:17]
	v_lshl_add_u64 v[108:109], v[108:109], 0, v[114:115]
	v_cvt_pk_f16_f32 v113, v74, v74
	global_store_short v[108:109], v113, off offset:3072
	v_cvt_pk_f16_f32 v113, v78, v78
	global_store_short v[108:109], v113, off offset:1024
	v_cvt_pk_f16_f32 v113, v82, v82
	global_store_short v[108:109], v113, off offset:-1024
	v_cvt_pk_f16_f32 v113, v86, v86
	global_store_short v[108:109], v113, off offset:-3072
	v_cvt_pk_f16_f32 v113, v90, v90
	global_store_short v[106:107], v113, off offset:3072
	v_cvt_pk_f16_f32 v113, v94, v94
	global_store_short v[106:107], v113, off offset:1024
	v_cvt_pk_f16_f32 v113, v98, v98
	global_store_short v[106:107], v113, off offset:-1024
	v_cvt_pk_f16_f32 v113, v102, v102
	global_store_short v[106:107], v113, off offset:-3072
	s_branch .LBB0_2081

; template <int RB, int EK, int D> __device__ __forceinline__ void rwkv_item_ws(const Params& p, int j, int s, int hd, int rq, char* shm_) {
;     ...
;     for (int ci = 0; ci < nch; ++ci) {
;       int chunk = d == 0 ? ci : nch - 1 - ci;
;       int buf = ci & 1;
;       const float* sr = arr(buf, 0); const float* sv = arr(buf, 1); const float* sk = arr(buf, 2);
;       const float* skk = arr(buf, 3); const float* sb = arr(buf, 4); const float* sw = arr(buf, 5);
;       f32x2 kkc_[NP], wc_[NP], bc_[NP], k2c_[NP], rc_[NP];
;       float vvc[RB];
;       auto ld = [&](int stp, f32x2* kk_, f32x2* w_, f32x2* b_, f32x2* k2_, f32x2* r_, float* vv_) {
;         int t = d == 0 ? stp : CH - 1 - stp;
;         int o = t * 64 + kq * EK;
; #pragma unroll
;         for (int e = 0; e < NP; ++e) {
;           kk_[e] = *reinterpret_cast<const f32x2*>(skk + o + 2 * e);
;           w_[e] = *reinterpret_cast<const f32x2*>(sw + o + 2 * e);
;           b_[e] = *reinterpret_cast<const f32x2*>(sb + o + 2 * e);
;           k2_[e] = *reinterpret_cast<const f32x2*>(sk + o + 2 * e);
;           r_[e] = *reinterpret_cast<const f32x2*>(sr + o + 2 * e);
;         }
; #pragma unroll
;         for (int rb = 0; rb < RB; ++rb) vv_[rb] = sv[t * 64 + row0 + rb];
;       };
;       ld(0, kkc_, wc_, bc_, k2c_, rc_, vvc);
;       float ys[CH][RB];
; #pragma unroll
;       for (int stp = 0; stp < CH; ++stp) {
;         f32x2 kkn_[NP], wn_[NP], bn_[NP], k2n_[NP], rn_[NP];
;         float vvn[RB];
;         ld(stp < CH - 1 ? stp + 1 : CH - 1, kkn_, wn_, bn_, k2n_, rn_, vvn);
; #pragma unroll
;         for (int rb = 0; rb < RB; ++rb) {
;           f32x2 acc2 = S[rb][0] * kkc_[0] + S[rb][1] * kkc_[1];
;           if constexpr (NP == 4) acc2 += S[rb][2] * kkc_[2] + S[rb][3] * kkc_[3];
;           float sa = reduce_row<LPR>(-(acc2[0] + acc2[1]));
;           f32x2 sa2 = {sa, sa}, vv2 = {vvc[rb], vvc[rb]};
; #pragma unroll
;           for (int e = 0; e < NP; ++e) S[rb][e] = S[rb][e] * wc_[e] + sa2 * bc_[e] + vv2 * k2c_[e];
;           f32x2 y2 = S[rb][0] * rc_[0] + S[rb][1] * rc_[1];
;           if constexpr (NP == 4) y2 += S[rb][2] * rc_[2] + S[rb][3] * rc_[3];
;           ys[stp][rb] = reduce_row<LPR>(y2[0] + y2[1]);
;         }
.LBB0_2100:
	s_bitcmp1_b32 s14, 0
	s_cselect_b32 s5, 0x6000, 0
	s_addk_i32 s5, 0x110
	v_lshl_add_u32 v34, v2, 2, s5
	v_add_u32_e32 v35, 0x1000, v34
	v_lshl_add_u32 v3, v0, 2, s5
	ds_read_b128 v[6:9], v3 offset:12288
	ds_read_b128 v[10:13], v3 offset:20480
	ds_read_b64 v[26:27], v34 offset:4096
	ds_read_b128 v[18:21], v3 offset:8192
	ds_read_b128 v[14:17], v3 offset:16384
	ds_read_b128 v[22:25], v3 offset:0
	ds_read_b128 v[36:39], v3 offset:12544
	ds_read_b128 v[40:43], v3 offset:20736
	ds_read_b64 v[56:57], v34 offset:4352
	ds_read_b128 v[48:51], v3 offset:8448
	ds_read_b128 v[44:47], v3 offset:16640
	ds_read_b128 v[52:55], v3 offset:256
	s_waitcnt lgkmcnt(6)
	v_pk_mul_f32 v[28:29], v[58:59], v[6:7] op_sel_hi:[1,0]
	v_pk_fma_f32 v[28:29], v[60:61], v[6:7], v[28:29] op_sel:[0,1,0]
	v_pk_fma_f32 v[28:29], v[62:63], v[8:9], v[28:29] op_sel_hi:[1,0,1]
	v_pk_fma_f32 v[28:29], v[64:65], v[8:9], v[28:29] op_sel:[0,1,0]
	v_pk_mul_f32 v[66:67], v[58:59], v[10:11] op_sel_hi:[1,0]
	v_pk_mul_f32 v[68:69], v[60:61], v[10:11] op_sel:[0,1]
	v_add_f32_dpp v28, v28, v28 quad_perm:[1,0,3,2] row_mask:0xf bank_mask:0xf bound_ctrl:1
	v_add_f32_dpp v29, v29, v29 quad_perm:[1,0,3,2] row_mask:0xf bank_mask:0xf bound_ctrl:1
	v_pk_mul_f32 v[70:71], v[62:63], v[12:13] op_sel_hi:[1,0]
	v_add_f32_dpp v28, v28, v28 quad_perm:[2,3,0,1] row_mask:0xf bank_mask:0xf bound_ctrl:1
	v_add_f32_dpp v29, v29, v29 quad_perm:[2,3,0,1] row_mask:0xf bank_mask:0xf bound_ctrl:1
	v_pk_mul_f32 v[72:73], v[64:65], v[12:13] op_sel:[0,1]
	v_add_f32_dpp v28, v28, v28 row_half_mirror row_mask:0xf bank_mask:0xf bound_ctrl:1
	v_add_f32_dpp v29, v29, v29 row_half_mirror row_mask:0xf bank_mask:0xf bound_ctrl:1
	v_pk_fma_f32 v[66:67], v[26:27], v[18:19], v[66:67] op_sel_hi:[1,0,1]
	v_add_f32_dpp v28, v28, v28 row_mirror row_mask:0xf bank_mask:0xf bound_ctrl:1
	v_add_f32_dpp v29, v29, v29 row_mirror row_mask:0xf bank_mask:0xf bound_ctrl:1
	v_pk_fma_f32 v[68:69], v[26:27], v[18:19], v[68:69] op_sel:[0,1,0]
	v_pk_fma_f32 v[70:71], v[26:27], v[20:21], v[70:71] op_sel_hi:[1,0,1]
	v_pk_fma_f32 v[72:73], v[26:27], v[20:21], v[72:73] op_sel:[0,1,0]
	v_pk_fma_f32 v[58:59], v[28:29], v[14:15], v[66:67] op_sel_hi:[1,0,1] neg_lo:[1,0,0] neg_hi:[1,0,0]
	v_pk_fma_f32 v[60:61], v[28:29], v[14:15], v[68:69] op_sel:[0,1,0] neg_lo:[1,0,0] neg_hi:[1,0,0]
	v_pk_fma_f32 v[62:63], v[28:29], v[16:17], v[70:71] op_sel_hi:[1,0,1] neg_lo:[1,0,0] neg_hi:[1,0,0]
	v_pk_fma_f32 v[64:65], v[28:29], v[16:17], v[72:73] op_sel:[0,1,0] neg_lo:[1,0,0] neg_hi:[1,0,0]
	v_pk_mul_f32 v[74:75], v[58:59], v[22:23] op_sel_hi:[1,0]
	v_pk_fma_f32 v[74:75], v[60:61], v[22:23], v[74:75] op_sel:[0,1,0]
	v_pk_fma_f32 v[74:75], v[62:63], v[24:25], v[74:75] op_sel_hi:[1,0,1]
	v_pk_fma_f32 v[74:75], v[64:65], v[24:25], v[74:75] op_sel:[0,1,0]
	ds_read_b128 v[6:9], v3 offset:12800
	ds_read_b128 v[10:13], v3 offset:20992
	ds_read_b64 v[26:27], v34 offset:4608
	ds_read_b128 v[18:21], v3 offset:8704
	ds_read_b128 v[14:17], v3 offset:16896
	ds_read_b128 v[22:25], v3 offset:512
	s_waitcnt lgkmcnt(6)
	v_pk_mul_f32 v[28:29], v[58:59], v[36:37] op_sel_hi:[1,0]
	v_pk_fma_f32 v[28:29], v[60:61], v[36:37], v[28:29] op_sel:[0,1,0]
	v_pk_fma_f32 v[28:29], v[62:63], v[38:39], v[28:29] op_sel_hi:[1,0,1]
	v_pk_fma_f32 v[28:29], v[64:65], v[38:39], v[28:29] op_sel:[0,1,0]
	v_pk_mul_f32 v[66:67], v[58:59], v[40:41] op_sel_hi:[1,0]
	v_pk_mul_f32 v[68:69], v[60:61], v[40:41] op_sel:[0,1]
	v_add_f32_dpp v28, v28, v28 quad_perm:[1,0,3,2] row_mask:0xf bank_mask:0xf bound_ctrl:1
	v_add_f32_dpp v29, v29, v29 quad_perm:[1,0,3,2] row_mask:0xf bank_mask:0xf bound_ctrl:1
	v_pk_mul_f32 v[70:71], v[62:63], v[42:43] op_sel_hi:[1,0]
	v_add_f32_dpp v28, v28, v28 quad_perm:[2,3,0,1] row_mask:0xf bank_mask:0xf bound_ctrl:1
	v_add_f32_dpp v29, v29, v29 quad_perm:[2,3,0,1] row_mask:0xf bank_mask:0xf bound_ctrl:1
	v_pk_mul_f32 v[72:73], v[64:65], v[42:43] op_sel:[0,1]
	v_add_f32_dpp v28, v28, v28 row_half_mirror row_mask:0xf bank_mask:0xf bound_ctrl:1
	v_add_f32_dpp v29, v29, v29 row_half_mirror row_mask:0xf bank_mask:0xf bound_ctrl:1
	v_pk_fma_f32 v[66:67], v[56:57], v[48:49], v[66:67] op_sel_hi:[1,0,1]
	v_add_f32_dpp v28, v28, v28 row_mirror row_mask:0xf bank_mask:0xf bound_ctrl:1
	v_add_f32_dpp v29, v29, v29 row_mirror row_mask:0xf bank_mask:0xf bound_ctrl:1
	v_pk_fma_f32 v[68:69], v[56:57], v[48:49], v[68:69] op_sel:[0,1,0]
	v_pk_fma_f32 v[70:71], v[56:57], v[50:51], v[70:71] op_sel_hi:[1,0,1]
	v_pk_fma_f32 v[72:73], v[56:57], v[50:51], v[72:73] op_sel:[0,1,0]
	v_pk_fma_f32 v[58:59], v[28:29], v[44:45], v[66:67] op_sel_hi:[1,0,1] neg_lo:[1,0,0] neg_hi:[1,0,0]
	v_pk_fma_f32 v[60:61], v[28:29], v[44:45], v[68:69] op_sel:[0,1,0] neg_lo:[1,0,0] neg_hi:[1,0,0]
	v_pk_fma_f32 v[62:63], v[28:29], v[46:47], v[70:71] op_sel_hi:[1,0,1] neg_lo:[1,0,0] neg_hi:[1,0,0]
	v_pk_fma_f32 v[64:65], v[28:29], v[46:47], v[72:73] op_sel:[0,1,0] neg_lo:[1,0,0] neg_hi:[1,0,0]
	v_pk_mul_f32 v[76:77], v[58:59], v[52:53] op_sel_hi:[1,0]
	v_pk_fma_f32 v[76:77], v[60:61], v[52:53], v[76:77] op_sel:[0,1,0]
	v_pk_fma_f32 v[76:77], v[62:63], v[54:55], v[76:77] op_sel_hi:[1,0,1]
	v_pk_fma_f32 v[76:77], v[64:65], v[54:55], v[76:77] op_sel:[0,1,0]
	ds_read_b128 v[36:39], v3 offset:13056
	ds_read_b128 v[40:43], v3 offset:21248
	ds_read_b64 v[56:57], v34 offset:4864
	ds_read_b128 v[48:51], v3 offset:8960
	ds_read_b128 v[44:47], v3 offset:17152
	ds_read_b128 v[52:55], v3 offset:768
	s_waitcnt lgkmcnt(6)
; template <int RB, int EK, int D> __device__ __forceinline__ void rwkv_item_ws(const Params& p, int j, int s, int hd, int rq, char* shm_) {
;     ...
;       auto ld = [&](int stp, f32x2* kk_, f32x2* w_, f32x2* b_, f32x2* k2_, f32x2* r_, float* vv_) {
;         int t = d == 0 ? stp : CH - 1 - stp;
;         int o = t * 64 + kq * EK;
; #pragma unroll
;         for (int e = 0; e < NP; ++e) {
;           kk_[e] = *reinterpret_cast<const f32x2*>(skk + o + 2 * e);
;           w_[e] = *reinterpret_cast<const f32x2*>(sw + o + 2 * e);
;           b_[e] = *reinterpret_cast<const f32x2*>(sb + o + 2 * e);
;           k2_[e] = *reinterpret_cast<const f32x2*>(sk + o + 2 * e);
;           r_[e] = *reinterpret_cast<const f32x2*>(sr + o + 2 * e);
;         }
; #pragma unroll
;         for (int rb = 0; rb < RB; ++rb) vv_[rb] = sv[t * 64 + row0 + rb];
;       };
;       ld(0, kkc_, wc_, bc_, k2c_, rc_, vvc);
;       float ys[CH][RB];
; #pragma unroll
;       for (int stp = 0; stp < CH; ++stp) {
;         f32x2 kkn_[NP], wn_[NP], bn_[NP], k2n_[NP], rn_[NP];
;         float vvn[RB];
;         ld(stp < CH - 1 ? stp + 1 : CH - 1, kkn_, wn_, bn_, k2n_, rn_, vvn);
; #pragma unroll
;         for (int rb = 0; rb < RB; ++rb) {
;           f32x2 acc2 = S[rb][0] * kkc_[0] + S[rb][1] * kkc_[1];
;           if constexpr (NP == 4) acc2 += S[rb][2] * kkc_[2] + S[rb][3] * kkc_[3];
;           float sa = reduce_row<LPR>(-(acc2[0] + acc2[1]));
;           f32x2 sa2 = {sa, sa}, vv2 = {vvc[rb], vvc[rb]};
; #pragma unroll
;           for (int e = 0; e < NP; ++e) S[rb][e] = S[rb][e] * wc_[e] + sa2 * bc_[e] + vv2 * k2c_[e];
;           f32x2 y2 = S[rb][0] * rc_[0] + S[rb][1] * rc_[1];
;           if constexpr (NP == 4) y2 += S[rb][2] * rc_[2] + S[rb][3] * rc_[3];
;           ys[stp][rb] = reduce_row<LPR>(y2[0] + y2[1]);
;         }
	v_pk_mul_f32 v[28:29], v[58:59], v[6:7] op_sel_hi:[1,0]
	v_pk_fma_f32 v[28:29], v[60:61], v[6:7], v[28:29] op_sel:[0,1,0]
	v_pk_fma_f32 v[28:29], v[62:63], v[8:9], v[28:29] op_sel_hi:[1,0,1]
	v_pk_fma_f32 v[28:29], v[64:65], v[8:9], v[28:29] op_sel:[0,1,0]
	v_pk_mul_f32 v[66:67], v[58:59], v[10:11] op_sel_hi:[1,0]
	v_pk_mul_f32 v[68:69], v[60:61], v[10:11] op_sel:[0,1]
	v_add_f32_dpp v28, v28, v28 quad_perm:[1,0,3,2] row_mask:0xf bank_mask:0xf bound_ctrl:1
	v_add_f32_dpp v29, v29, v29 quad_perm:[1,0,3,2] row_mask:0xf bank_mask:0xf bound_ctrl:1
	v_pk_mul_f32 v[70:71], v[62:63], v[12:13] op_sel_hi:[1,0]
	v_add_f32_dpp v28, v28, v28 quad_perm:[2,3,0,1] row_mask:0xf bank_mask:0xf bound_ctrl:1
	v_add_f32_dpp v29, v29, v29 quad_perm:[2,3,0,1] row_mask:0xf bank_mask:0xf bound_ctrl:1
	v_pk_mul_f32 v[72:73], v[64:65], v[12:13] op_sel:[0,1]
	v_add_f32_dpp v28, v28, v28 row_half_mirror row_mask:0xf bank_mask:0xf bound_ctrl:1
	v_add_f32_dpp v29, v29, v29 row_half_mirror row_mask:0xf bank_mask:0xf bound_ctrl:1
	v_pk_fma_f32 v[66:67], v[26:27], v[18:19], v[66:67] op_sel_hi:[1,0,1]
	v_add_f32_dpp v28, v28, v28 row_mirror row_mask:0xf bank_mask:0xf bound_ctrl:1
	v_add_f32_dpp v29, v29, v29 row_mirror row_mask:0xf bank_mask:0xf bound_ctrl:1
	v_pk_fma_f32 v[68:69], v[26:27], v[18:19], v[68:69] op_sel:[0,1,0]
	v_pk_fma_f32 v[70:71], v[26:27], v[20:21], v[70:71] op_sel_hi:[1,0,1]
	v_pk_fma_f32 v[72:73], v[26:27], v[20:21], v[72:73] op_sel:[0,1,0]
	v_pk_fma_f32 v[58:59], v[28:29], v[14:15], v[66:67] op_sel_hi:[1,0,1] neg_lo:[1,0,0] neg_hi:[1,0,0]
	v_pk_fma_f32 v[60:61], v[28:29], v[14:15], v[68:69] op_sel:[0,1,0] neg_lo:[1,0,0] neg_hi:[1,0,0]
	v_pk_fma_f32 v[62:63], v[28:29], v[16:17], v[70:71] op_sel_hi:[1,0,1] neg_lo:[1,0,0] neg_hi:[1,0,0]
	v_pk_fma_f32 v[64:65], v[28:29], v[16:17], v[72:73] op_sel:[0,1,0] neg_lo:[1,0,0] neg_hi:[1,0,0]
	v_pk_mul_f32 v[78:79], v[58:59], v[22:23] op_sel_hi:[1,0]
	v_pk_fma_f32 v[78:79], v[60:61], v[22:23], v[78:79] op_sel:[0,1,0]
	v_pk_fma_f32 v[78:79], v[62:63], v[24:25], v[78:79] op_sel_hi:[1,0,1]
	v_pk_fma_f32 v[78:79], v[64:65], v[24:25], v[78:79] op_sel:[0,1,0]
	ds_read_b128 v[6:9], v3 offset:13312
	ds_read_b128 v[10:13], v3 offset:21504
	ds_read_b64 v[26:27], v34 offset:5120
	ds_read_b128 v[18:21], v3 offset:9216
	ds_read_b128 v[14:17], v3 offset:17408
	ds_read_b128 v[22:25], v3 offset:1024
	s_waitcnt lgkmcnt(6)
	v_pk_mul_f32 v[28:29], v[58:59], v[36:37] op_sel_hi:[1,0]
	v_pk_fma_f32 v[28:29], v[60:61], v[36:37], v[28:29] op_sel:[0,1,0]
	v_pk_fma_f32 v[28:29], v[62:63], v[38:39], v[28:29] op_sel_hi:[1,0,1]
	v_pk_fma_f32 v[28:29], v[64:65], v[38:39], v[28:29] op_sel:[0,1,0]
	v_pk_mul_f32 v[66:67], v[58:59], v[40:41] op_sel_hi:[1,0]
	v_pk_mul_f32 v[68:69], v[60:61], v[40:41] op_sel:[0,1]
	v_add_f32_dpp v28, v28, v28 quad_perm:[1,0,3,2] row_mask:0xf bank_mask:0xf bound_ctrl:1
	v_add_f32_dpp v29, v29, v29 quad_perm:[1,0,3,2] row_mask:0xf bank_mask:0xf bound_ctrl:1
	v_pk_mul_f32 v[70:71], v[62:63], v[42:43] op_sel_hi:[1,0]
	v_add_f32_dpp v28, v28, v28 quad_perm:[2,3,0,1] row_mask:0xf bank_mask:0xf bound_ctrl:1
	v_add_f32_dpp v29, v29, v29 quad_perm:[2,3,0,1] row_mask:0xf bank_mask:0xf bound_ctrl:1
	v_pk_mul_f32 v[72:73], v[64:65], v[42:43] op_sel:[0,1]
	v_add_f32_dpp v28, v28, v28 row_half_mirror row_mask:0xf bank_mask:0xf bound_ctrl:1
	v_add_f32_dpp v29, v29, v29 row_half_mirror row_mask:0xf bank_mask:0xf bound_ctrl:1
	v_pk_fma_f32 v[66:67], v[56:57], v[48:49], v[66:67] op_sel_hi:[1,0,1]
	v_add_f32_dpp v28, v28, v28 row_mirror row_mask:0xf bank_mask:0xf bound_ctrl:1
	v_add_f32_dpp v29, v29, v29 row_mirror row_mask:0xf bank_mask:0xf bound_ctrl:1
	v_pk_fma_f32 v[68:69], v[56:57], v[48:49], v[68:69] op_sel:[0,1,0]
	v_pk_fma_f32 v[70:71], v[56:57], v[50:51], v[70:71] op_sel_hi:[1,0,1]
	v_pk_fma_f32 v[72:73], v[56:57], v[50:51], v[72:73] op_sel:[0,1,0]
	v_pk_fma_f32 v[58:59], v[28:29], v[44:45], v[66:67] op_sel_hi:[1,0,1] neg_lo:[1,0,0] neg_hi:[1,0,0]
	v_pk_fma_f32 v[60:61], v[28:29], v[44:45], v[68:69] op_sel:[0,1,0] neg_lo:[1,0,0] neg_hi:[1,0,0]
	v_pk_fma_f32 v[62:63], v[28:29], v[46:47], v[70:71] op_sel_hi:[1,0,1] neg_lo:[1,0,0] neg_hi:[1,0,0]
	v_pk_fma_f32 v[64:65], v[28:29], v[46:47], v[72:73] op_sel:[0,1,0] neg_lo:[1,0,0] neg_hi:[1,0,0]
	v_pk_mul_f32 v[80:81], v[58:59], v[52:53] op_sel_hi:[1,0]
	v_pk_fma_f32 v[80:81], v[60:61], v[52:53], v[80:81] op_sel:[0,1,0]
	v_pk_fma_f32 v[80:81], v[62:63], v[54:55], v[80:81] op_sel_hi:[1,0,1]
	v_pk_fma_f32 v[80:81], v[64:65], v[54:55], v[80:81] op_sel:[0,1,0]
	ds_read_b128 v[36:39], v3 offset:13568
	ds_read_b128 v[40:43], v3 offset:21760
	ds_read_b64 v[56:57], v34 offset:5376
	ds_read_b128 v[48:51], v3 offset:9472
	ds_read_b128 v[44:47], v3 offset:17664
	ds_read_b128 v[52:55], v3 offset:1280
	s_waitcnt lgkmcnt(6)
; template <int RB, int EK, int D> __device__ __forceinline__ void rwkv_item_ws(const Params& p, int j, int s, int hd, int rq, char* shm_) {
;     ...
;       auto ld = [&](int stp, f32x2* kk_, f32x2* w_, f32x2* b_, f32x2* k2_, f32x2* r_, float* vv_) {
;         int t = d == 0 ? stp : CH - 1 - stp;
;         int o = t * 64 + kq * EK;
; #pragma unroll
;         for (int e = 0; e < NP; ++e) {
;           kk_[e] = *reinterpret_cast<const f32x2*>(skk + o + 2 * e);
;           w_[e] = *reinterpret_cast<const f32x2*>(sw + o + 2 * e);
;           b_[e] = *reinterpret_cast<const f32x2*>(sb + o + 2 * e);
;           k2_[e] = *reinterpret_cast<const f32x2*>(sk + o + 2 * e);
;           r_[e] = *reinterpret_cast<const f32x2*>(sr + o + 2 * e);
;         }
; #pragma unroll
;         for (int rb = 0; rb < RB; ++rb) vv_[rb] = sv[t * 64 + row0 + rb];
;       };
;       ld(0, kkc_, wc_, bc_, k2c_, rc_, vvc);
;       float ys[CH][RB];
; #pragma unroll
;       for (int stp = 0; stp < CH; ++stp) {
;         f32x2 kkn_[NP], wn_[NP], bn_[NP], k2n_[NP], rn_[NP];
;         float vvn[RB];
;         ld(stp < CH - 1 ? stp + 1 : CH - 1, kkn_, wn_, bn_, k2n_, rn_, vvn);
; #pragma unroll
;         for (int rb = 0; rb < RB; ++rb) {
;           f32x2 acc2 = S[rb][0] * kkc_[0] + S[rb][1] * kkc_[1];
;           if constexpr (NP == 4) acc2 += S[rb][2] * kkc_[2] + S[rb][3] * kkc_[3];
;           float sa = reduce_row<LPR>(-(acc2[0] + acc2[1]));
;           f32x2 sa2 = {sa, sa}, vv2 = {vvc[rb], vvc[rb]};
; #pragma unroll
;           for (int e = 0; e < NP; ++e) S[rb][e] = S[rb][e] * wc_[e] + sa2 * bc_[e] + vv2 * k2c_[e];
;           f32x2 y2 = S[rb][0] * rc_[0] + S[rb][1] * rc_[1];
;           if constexpr (NP == 4) y2 += S[rb][2] * rc_[2] + S[rb][3] * rc_[3];
;           ys[stp][rb] = reduce_row<LPR>(y2[0] + y2[1]);
;         }
	v_pk_mul_f32 v[28:29], v[58:59], v[6:7] op_sel_hi:[1,0]
	v_pk_fma_f32 v[28:29], v[60:61], v[6:7], v[28:29] op_sel:[0,1,0]
	v_pk_fma_f32 v[28:29], v[62:63], v[8:9], v[28:29] op_sel_hi:[1,0,1]
	v_pk_fma_f32 v[28:29], v[64:65], v[8:9], v[28:29] op_sel:[0,1,0]
	v_pk_mul_f32 v[66:67], v[58:59], v[10:11] op_sel_hi:[1,0]
	v_pk_mul_f32 v[68:69], v[60:61], v[10:11] op_sel:[0,1]
	v_add_f32_dpp v28, v28, v28 quad_perm:[1,0,3,2] row_mask:0xf bank_mask:0xf bound_ctrl:1
	v_add_f32_dpp v29, v29, v29 quad_perm:[1,0,3,2] row_mask:0xf bank_mask:0xf bound_ctrl:1
	v_pk_mul_f32 v[70:71], v[62:63], v[12:13] op_sel_hi:[1,0]
	v_add_f32_dpp v28, v28, v28 quad_perm:[2,3,0,1] row_mask:0xf bank_mask:0xf bound_ctrl:1
	v_add_f32_dpp v29, v29, v29 quad_perm:[2,3,0,1] row_mask:0xf bank_mask:0xf bound_ctrl:1
	v_pk_mul_f32 v[72:73], v[64:65], v[12:13] op_sel:[0,1]
	v_add_f32_dpp v28, v28, v28 row_half_mirror row_mask:0xf bank_mask:0xf bound_ctrl:1
	v_add_f32_dpp v29, v29, v29 row_half_mirror row_mask:0xf bank_mask:0xf bound_ctrl:1
	v_pk_fma_f32 v[66:67], v[26:27], v[18:19], v[66:67] op_sel_hi:[1,0,1]
	v_add_f32_dpp v28, v28, v28 row_mirror row_mask:0xf bank_mask:0xf bound_ctrl:1
	v_add_f32_dpp v29, v29, v29 row_mirror row_mask:0xf bank_mask:0xf bound_ctrl:1
	v_pk_fma_f32 v[68:69], v[26:27], v[18:19], v[68:69] op_sel:[0,1,0]
	v_pk_fma_f32 v[70:71], v[26:27], v[20:21], v[70:71] op_sel_hi:[1,0,1]
	v_pk_fma_f32 v[72:73], v[26:27], v[20:21], v[72:73] op_sel:[0,1,0]
	v_pk_fma_f32 v[58:59], v[28:29], v[14:15], v[66:67] op_sel_hi:[1,0,1] neg_lo:[1,0,0] neg_hi:[1,0,0]
	v_pk_fma_f32 v[60:61], v[28:29], v[14:15], v[68:69] op_sel:[0,1,0] neg_lo:[1,0,0] neg_hi:[1,0,0]
	v_pk_fma_f32 v[62:63], v[28:29], v[16:17], v[70:71] op_sel_hi:[1,0,1] neg_lo:[1,0,0] neg_hi:[1,0,0]
	v_pk_fma_f32 v[64:65], v[28:29], v[16:17], v[72:73] op_sel:[0,1,0] neg_lo:[1,0,0] neg_hi:[1,0,0]
	v_pk_mul_f32 v[82:83], v[58:59], v[22:23] op_sel_hi:[1,0]
	v_pk_fma_f32 v[82:83], v[60:61], v[22:23], v[82:83] op_sel:[0,1,0]
	v_pk_fma_f32 v[82:83], v[62:63], v[24:25], v[82:83] op_sel_hi:[1,0,1]
	v_pk_fma_f32 v[82:83], v[64:65], v[24:25], v[82:83] op_sel:[0,1,0]
	ds_read_b128 v[6:9], v3 offset:13824
	ds_read_b128 v[10:13], v3 offset:22016
	ds_read_b64 v[26:27], v34 offset:5632
	ds_read_b128 v[18:21], v3 offset:9728
	ds_read_b128 v[14:17], v3 offset:17920
	ds_read_b128 v[22:25], v3 offset:1536
	s_waitcnt lgkmcnt(6)
	v_pk_mul_f32 v[28:29], v[58:59], v[36:37] op_sel_hi:[1,0]
	v_pk_fma_f32 v[28:29], v[60:61], v[36:37], v[28:29] op_sel:[0,1,0]
	v_pk_fma_f32 v[28:29], v[62:63], v[38:39], v[28:29] op_sel_hi:[1,0,1]
	v_pk_fma_f32 v[28:29], v[64:65], v[38:39], v[28:29] op_sel:[0,1,0]
	v_pk_mul_f32 v[66:67], v[58:59], v[40:41] op_sel_hi:[1,0]
	v_pk_mul_f32 v[68:69], v[60:61], v[40:41] op_sel:[0,1]
	v_add_f32_dpp v28, v28, v28 quad_perm:[1,0,3,2] row_mask:0xf bank_mask:0xf bound_ctrl:1
	v_add_f32_dpp v29, v29, v29 quad_perm:[1,0,3,2] row_mask:0xf bank_mask:0xf bound_ctrl:1
	v_pk_mul_f32 v[70:71], v[62:63], v[42:43] op_sel_hi:[1,0]
	v_add_f32_dpp v28, v28, v28 quad_perm:[2,3,0,1] row_mask:0xf bank_mask:0xf bound_ctrl:1
	v_add_f32_dpp v29, v29, v29 quad_perm:[2,3,0,1] row_mask:0xf bank_mask:0xf bound_ctrl:1
	v_pk_mul_f32 v[72:73], v[64:65], v[42:43] op_sel:[0,1]
	v_add_f32_dpp v28, v28, v28 row_half_mirror row_mask:0xf bank_mask:0xf bound_ctrl:1
	v_add_f32_dpp v29, v29, v29 row_half_mirror row_mask:0xf bank_mask:0xf bound_ctrl:1
	v_pk_fma_f32 v[66:67], v[56:57], v[48:49], v[66:67] op_sel_hi:[1,0,1]
	v_add_f32_dpp v28, v28, v28 row_mirror row_mask:0xf bank_mask:0xf bound_ctrl:1
	v_add_f32_dpp v29, v29, v29 row_mirror row_mask:0xf bank_mask:0xf bound_ctrl:1
	v_pk_fma_f32 v[68:69], v[56:57], v[48:49], v[68:69] op_sel:[0,1,0]
	v_pk_fma_f32 v[70:71], v[56:57], v[50:51], v[70:71] op_sel_hi:[1,0,1]
	v_pk_fma_f32 v[72:73], v[56:57], v[50:51], v[72:73] op_sel:[0,1,0]
	v_pk_fma_f32 v[58:59], v[28:29], v[44:45], v[66:67] op_sel_hi:[1,0,1] neg_lo:[1,0,0] neg_hi:[1,0,0]
	v_pk_fma_f32 v[60:61], v[28:29], v[44:45], v[68:69] op_sel:[0,1,0] neg_lo:[1,0,0] neg_hi:[1,0,0]
	v_pk_fma_f32 v[62:63], v[28:29], v[46:47], v[70:71] op_sel_hi:[1,0,1] neg_lo:[1,0,0] neg_hi:[1,0,0]
	v_pk_fma_f32 v[64:65], v[28:29], v[46:47], v[72:73] op_sel:[0,1,0] neg_lo:[1,0,0] neg_hi:[1,0,0]
	v_pk_mul_f32 v[84:85], v[58:59], v[52:53] op_sel_hi:[1,0]
	v_pk_fma_f32 v[84:85], v[60:61], v[52:53], v[84:85] op_sel:[0,1,0]
	v_pk_fma_f32 v[84:85], v[62:63], v[54:55], v[84:85] op_sel_hi:[1,0,1]
	v_pk_fma_f32 v[84:85], v[64:65], v[54:55], v[84:85] op_sel:[0,1,0]
	ds_read_b128 v[36:39], v3 offset:14080
	ds_read_b128 v[40:43], v3 offset:22272
	ds_read_b64 v[56:57], v34 offset:5888
	ds_read_b128 v[48:51], v3 offset:9984
	ds_read_b128 v[44:47], v3 offset:18176
	ds_read_b128 v[52:55], v3 offset:1792
	s_waitcnt lgkmcnt(6)
; template <int RB, int EK, int D> __device__ __forceinline__ void rwkv_item_ws(const Params& p, int j, int s, int hd, int rq, char* shm_) {
;     ...
;       auto ld = [&](int stp, f32x2* kk_, f32x2* w_, f32x2* b_, f32x2* k2_, f32x2* r_, float* vv_) {
;         int t = d == 0 ? stp : CH - 1 - stp;
;         int o = t * 64 + kq * EK;
; #pragma unroll
;         for (int e = 0; e < NP; ++e) {
;           kk_[e] = *reinterpret_cast<const f32x2*>(skk + o + 2 * e);
;           w_[e] = *reinterpret_cast<const f32x2*>(sw + o + 2 * e);
;           b_[e] = *reinterpret_cast<const f32x2*>(sb + o + 2 * e);
;           k2_[e] = *reinterpret_cast<const f32x2*>(sk + o + 2 * e);
;           r_[e] = *reinterpret_cast<const f32x2*>(sr + o + 2 * e);
;         }
; #pragma unroll
;         for (int rb = 0; rb < RB; ++rb) vv_[rb] = sv[t * 64 + row0 + rb];
;       };
;       ld(0, kkc_, wc_, bc_, k2c_, rc_, vvc);
;       float ys[CH][RB];
; #pragma unroll
;       for (int stp = 0; stp < CH; ++stp) {
;         f32x2 kkn_[NP], wn_[NP], bn_[NP], k2n_[NP], rn_[NP];
;         float vvn[RB];
;         ld(stp < CH - 1 ? stp + 1 : CH - 1, kkn_, wn_, bn_, k2n_, rn_, vvn);
; #pragma unroll
;         for (int rb = 0; rb < RB; ++rb) {
;           f32x2 acc2 = S[rb][0] * kkc_[0] + S[rb][1] * kkc_[1];
;           if constexpr (NP == 4) acc2 += S[rb][2] * kkc_[2] + S[rb][3] * kkc_[3];
;           float sa = reduce_row<LPR>(-(acc2[0] + acc2[1]));
;           f32x2 sa2 = {sa, sa}, vv2 = {vvc[rb], vvc[rb]};
; #pragma unroll
;           for (int e = 0; e < NP; ++e) S[rb][e] = S[rb][e] * wc_[e] + sa2 * bc_[e] + vv2 * k2c_[e];
;           f32x2 y2 = S[rb][0] * rc_[0] + S[rb][1] * rc_[1];
;           if constexpr (NP == 4) y2 += S[rb][2] * rc_[2] + S[rb][3] * rc_[3];
;           ys[stp][rb] = reduce_row<LPR>(y2[0] + y2[1]);
;         }
	v_pk_mul_f32 v[28:29], v[58:59], v[6:7] op_sel_hi:[1,0]
	v_pk_fma_f32 v[28:29], v[60:61], v[6:7], v[28:29] op_sel:[0,1,0]
	v_pk_fma_f32 v[28:29], v[62:63], v[8:9], v[28:29] op_sel_hi:[1,0,1]
	v_pk_fma_f32 v[28:29], v[64:65], v[8:9], v[28:29] op_sel:[0,1,0]
	v_pk_mul_f32 v[66:67], v[58:59], v[10:11] op_sel_hi:[1,0]
	v_pk_mul_f32 v[68:69], v[60:61], v[10:11] op_sel:[0,1]
	v_add_f32_dpp v28, v28, v28 quad_perm:[1,0,3,2] row_mask:0xf bank_mask:0xf bound_ctrl:1
	v_add_f32_dpp v29, v29, v29 quad_perm:[1,0,3,2] row_mask:0xf bank_mask:0xf bound_ctrl:1
	v_pk_mul_f32 v[70:71], v[62:63], v[12:13] op_sel_hi:[1,0]
	v_add_f32_dpp v28, v28, v28 quad_perm:[2,3,0,1] row_mask:0xf bank_mask:0xf bound_ctrl:1
	v_add_f32_dpp v29, v29, v29 quad_perm:[2,3,0,1] row_mask:0xf bank_mask:0xf bound_ctrl:1
	v_pk_mul_f32 v[72:73], v[64:65], v[12:13] op_sel:[0,1]
	v_add_f32_dpp v28, v28, v28 row_half_mirror row_mask:0xf bank_mask:0xf bound_ctrl:1
	v_add_f32_dpp v29, v29, v29 row_half_mirror row_mask:0xf bank_mask:0xf bound_ctrl:1
	v_pk_fma_f32 v[66:67], v[26:27], v[18:19], v[66:67] op_sel_hi:[1,0,1]
	v_add_f32_dpp v28, v28, v28 row_mirror row_mask:0xf bank_mask:0xf bound_ctrl:1
	v_add_f32_dpp v29, v29, v29 row_mirror row_mask:0xf bank_mask:0xf bound_ctrl:1
	v_pk_fma_f32 v[68:69], v[26:27], v[18:19], v[68:69] op_sel:[0,1,0]
	v_pk_fma_f32 v[70:71], v[26:27], v[20:21], v[70:71] op_sel_hi:[1,0,1]
	v_pk_fma_f32 v[72:73], v[26:27], v[20:21], v[72:73] op_sel:[0,1,0]
	v_pk_fma_f32 v[58:59], v[28:29], v[14:15], v[66:67] op_sel_hi:[1,0,1] neg_lo:[1,0,0] neg_hi:[1,0,0]
	v_pk_fma_f32 v[60:61], v[28:29], v[14:15], v[68:69] op_sel:[0,1,0] neg_lo:[1,0,0] neg_hi:[1,0,0]
	v_pk_fma_f32 v[62:63], v[28:29], v[16:17], v[70:71] op_sel_hi:[1,0,1] neg_lo:[1,0,0] neg_hi:[1,0,0]
	v_pk_fma_f32 v[64:65], v[28:29], v[16:17], v[72:73] op_sel:[0,1,0] neg_lo:[1,0,0] neg_hi:[1,0,0]
	v_pk_mul_f32 v[86:87], v[58:59], v[22:23] op_sel_hi:[1,0]
	v_pk_fma_f32 v[86:87], v[60:61], v[22:23], v[86:87] op_sel:[0,1,0]
	v_pk_fma_f32 v[86:87], v[62:63], v[24:25], v[86:87] op_sel_hi:[1,0,1]
	v_pk_fma_f32 v[86:87], v[64:65], v[24:25], v[86:87] op_sel:[0,1,0]
	ds_read_b128 v[6:9], v3 offset:14336
	ds_read_b128 v[10:13], v3 offset:22528
	ds_read_b64 v[26:27], v34 offset:6144
	ds_read_b128 v[18:21], v3 offset:10240
	ds_read_b128 v[14:17], v3 offset:18432
	ds_read_b128 v[22:25], v3 offset:2048
	s_waitcnt lgkmcnt(6)
	v_pk_mul_f32 v[28:29], v[58:59], v[36:37] op_sel_hi:[1,0]
	v_pk_fma_f32 v[28:29], v[60:61], v[36:37], v[28:29] op_sel:[0,1,0]
	v_pk_fma_f32 v[28:29], v[62:63], v[38:39], v[28:29] op_sel_hi:[1,0,1]
	v_pk_fma_f32 v[28:29], v[64:65], v[38:39], v[28:29] op_sel:[0,1,0]
	v_pk_mul_f32 v[66:67], v[58:59], v[40:41] op_sel_hi:[1,0]
	v_pk_mul_f32 v[68:69], v[60:61], v[40:41] op_sel:[0,1]
	v_add_f32_dpp v28, v28, v28 quad_perm:[1,0,3,2] row_mask:0xf bank_mask:0xf bound_ctrl:1
	v_add_f32_dpp v29, v29, v29 quad_perm:[1,0,3,2] row_mask:0xf bank_mask:0xf bound_ctrl:1
	v_pk_mul_f32 v[70:71], v[62:63], v[42:43] op_sel_hi:[1,0]
	v_add_f32_dpp v28, v28, v28 quad_perm:[2,3,0,1] row_mask:0xf bank_mask:0xf bound_ctrl:1
	v_add_f32_dpp v29, v29, v29 quad_perm:[2,3,0,1] row_mask:0xf bank_mask:0xf bound_ctrl:1
	v_pk_mul_f32 v[72:73], v[64:65], v[42:43] op_sel:[0,1]
	v_add_f32_dpp v28, v28, v28 row_half_mirror row_mask:0xf bank_mask:0xf bound_ctrl:1
	v_add_f32_dpp v29, v29, v29 row_half_mirror row_mask:0xf bank_mask:0xf bound_ctrl:1
	v_pk_fma_f32 v[66:67], v[56:57], v[48:49], v[66:67] op_sel_hi:[1,0,1]
	v_add_f32_dpp v28, v28, v28 row_mirror row_mask:0xf bank_mask:0xf bound_ctrl:1
	v_add_f32_dpp v29, v29, v29 row_mirror row_mask:0xf bank_mask:0xf bound_ctrl:1
	v_pk_fma_f32 v[68:69], v[56:57], v[48:49], v[68:69] op_sel:[0,1,0]
	v_pk_fma_f32 v[70:71], v[56:57], v[50:51], v[70:71] op_sel_hi:[1,0,1]
	v_pk_fma_f32 v[72:73], v[56:57], v[50:51], v[72:73] op_sel:[0,1,0]
	v_pk_fma_f32 v[58:59], v[28:29], v[44:45], v[66:67] op_sel_hi:[1,0,1] neg_lo:[1,0,0] neg_hi:[1,0,0]
	v_pk_fma_f32 v[60:61], v[28:29], v[44:45], v[68:69] op_sel:[0,1,0] neg_lo:[1,0,0] neg_hi:[1,0,0]
	v_pk_fma_f32 v[62:63], v[28:29], v[46:47], v[70:71] op_sel_hi:[1,0,1] neg_lo:[1,0,0] neg_hi:[1,0,0]
	v_pk_fma_f32 v[64:65], v[28:29], v[46:47], v[72:73] op_sel:[0,1,0] neg_lo:[1,0,0] neg_hi:[1,0,0]
	v_pk_mul_f32 v[88:89], v[58:59], v[52:53] op_sel_hi:[1,0]
	v_pk_fma_f32 v[88:89], v[60:61], v[52:53], v[88:89] op_sel:[0,1,0]
	v_pk_fma_f32 v[88:89], v[62:63], v[54:55], v[88:89] op_sel_hi:[1,0,1]
	v_pk_fma_f32 v[88:89], v[64:65], v[54:55], v[88:89] op_sel:[0,1,0]
	ds_read_b128 v[36:39], v3 offset:14592
	ds_read_b128 v[40:43], v3 offset:22784
	ds_read_b64 v[56:57], v34 offset:6400
	ds_read_b128 v[48:51], v3 offset:10496
	ds_read_b128 v[44:47], v3 offset:18688
	ds_read_b128 v[52:55], v3 offset:2304
	s_waitcnt lgkmcnt(6)
; template <int RB, int EK, int D> __device__ __forceinline__ void rwkv_item_ws(const Params& p, int j, int s, int hd, int rq, char* shm_) {
;     ...
;       auto ld = [&](int stp, f32x2* kk_, f32x2* w_, f32x2* b_, f32x2* k2_, f32x2* r_, float* vv_) {
;         int t = d == 0 ? stp : CH - 1 - stp;
;         int o = t * 64 + kq * EK;
; #pragma unroll
;         for (int e = 0; e < NP; ++e) {
;           kk_[e] = *reinterpret_cast<const f32x2*>(skk + o + 2 * e);
;           w_[e] = *reinterpret_cast<const f32x2*>(sw + o + 2 * e);
;           b_[e] = *reinterpret_cast<const f32x2*>(sb + o + 2 * e);
;           k2_[e] = *reinterpret_cast<const f32x2*>(sk + o + 2 * e);
;           r_[e] = *reinterpret_cast<const f32x2*>(sr + o + 2 * e);
;         }
; #pragma unroll
;         for (int rb = 0; rb < RB; ++rb) vv_[rb] = sv[t * 64 + row0 + rb];
;       };
;       ld(0, kkc_, wc_, bc_, k2c_, rc_, vvc);
;       float ys[CH][RB];
; #pragma unroll
;       for (int stp = 0; stp < CH; ++stp) {
;         f32x2 kkn_[NP], wn_[NP], bn_[NP], k2n_[NP], rn_[NP];
;         float vvn[RB];
;         ld(stp < CH - 1 ? stp + 1 : CH - 1, kkn_, wn_, bn_, k2n_, rn_, vvn);
; #pragma unroll
;         for (int rb = 0; rb < RB; ++rb) {
;           f32x2 acc2 = S[rb][0] * kkc_[0] + S[rb][1] * kkc_[1];
;           if constexpr (NP == 4) acc2 += S[rb][2] * kkc_[2] + S[rb][3] * kkc_[3];
;           float sa = reduce_row<LPR>(-(acc2[0] + acc2[1]));
;           f32x2 sa2 = {sa, sa}, vv2 = {vvc[rb], vvc[rb]};
; #pragma unroll
;           for (int e = 0; e < NP; ++e) S[rb][e] = S[rb][e] * wc_[e] + sa2 * bc_[e] + vv2 * k2c_[e];
;           f32x2 y2 = S[rb][0] * rc_[0] + S[rb][1] * rc_[1];
;           if constexpr (NP == 4) y2 += S[rb][2] * rc_[2] + S[rb][3] * rc_[3];
;           ys[stp][rb] = reduce_row<LPR>(y2[0] + y2[1]);
;         }
	v_pk_mul_f32 v[28:29], v[58:59], v[6:7] op_sel_hi:[1,0]
	v_pk_fma_f32 v[28:29], v[60:61], v[6:7], v[28:29] op_sel:[0,1,0]
	v_pk_fma_f32 v[28:29], v[62:63], v[8:9], v[28:29] op_sel_hi:[1,0,1]
	v_pk_fma_f32 v[28:29], v[64:65], v[8:9], v[28:29] op_sel:[0,1,0]
	v_pk_mul_f32 v[66:67], v[58:59], v[10:11] op_sel_hi:[1,0]
	v_pk_mul_f32 v[68:69], v[60:61], v[10:11] op_sel:[0,1]
	v_add_f32_dpp v28, v28, v28 quad_perm:[1,0,3,2] row_mask:0xf bank_mask:0xf bound_ctrl:1
	v_add_f32_dpp v29, v29, v29 quad_perm:[1,0,3,2] row_mask:0xf bank_mask:0xf bound_ctrl:1
	v_pk_mul_f32 v[70:71], v[62:63], v[12:13] op_sel_hi:[1,0]
	v_add_f32_dpp v28, v28, v28 quad_perm:[2,3,0,1] row_mask:0xf bank_mask:0xf bound_ctrl:1
	v_add_f32_dpp v29, v29, v29 quad_perm:[2,3,0,1] row_mask:0xf bank_mask:0xf bound_ctrl:1
	v_pk_mul_f32 v[72:73], v[64:65], v[12:13] op_sel:[0,1]
	v_add_f32_dpp v28, v28, v28 row_half_mirror row_mask:0xf bank_mask:0xf bound_ctrl:1
	v_add_f32_dpp v29, v29, v29 row_half_mirror row_mask:0xf bank_mask:0xf bound_ctrl:1
	v_pk_fma_f32 v[66:67], v[26:27], v[18:19], v[66:67] op_sel_hi:[1,0,1]
	v_add_f32_dpp v28, v28, v28 row_mirror row_mask:0xf bank_mask:0xf bound_ctrl:1
	v_add_f32_dpp v29, v29, v29 row_mirror row_mask:0xf bank_mask:0xf bound_ctrl:1
	v_pk_fma_f32 v[68:69], v[26:27], v[18:19], v[68:69] op_sel:[0,1,0]
	v_pk_fma_f32 v[70:71], v[26:27], v[20:21], v[70:71] op_sel_hi:[1,0,1]
	v_pk_fma_f32 v[72:73], v[26:27], v[20:21], v[72:73] op_sel:[0,1,0]
	v_pk_fma_f32 v[58:59], v[28:29], v[14:15], v[66:67] op_sel_hi:[1,0,1] neg_lo:[1,0,0] neg_hi:[1,0,0]
	v_pk_fma_f32 v[60:61], v[28:29], v[14:15], v[68:69] op_sel:[0,1,0] neg_lo:[1,0,0] neg_hi:[1,0,0]
	v_pk_fma_f32 v[62:63], v[28:29], v[16:17], v[70:71] op_sel_hi:[1,0,1] neg_lo:[1,0,0] neg_hi:[1,0,0]
	v_pk_fma_f32 v[64:65], v[28:29], v[16:17], v[72:73] op_sel:[0,1,0] neg_lo:[1,0,0] neg_hi:[1,0,0]
	v_pk_mul_f32 v[90:91], v[58:59], v[22:23] op_sel_hi:[1,0]
	v_pk_fma_f32 v[90:91], v[60:61], v[22:23], v[90:91] op_sel:[0,1,0]
	v_pk_fma_f32 v[90:91], v[62:63], v[24:25], v[90:91] op_sel_hi:[1,0,1]
	v_pk_fma_f32 v[90:91], v[64:65], v[24:25], v[90:91] op_sel:[0,1,0]
	ds_read_b128 v[6:9], v3 offset:14848
	ds_read_b128 v[10:13], v3 offset:23040
	ds_read_b64 v[26:27], v34 offset:6656
	ds_read_b128 v[18:21], v3 offset:10752
	ds_read_b128 v[14:17], v3 offset:18944
	ds_read_b128 v[22:25], v3 offset:2560
	s_waitcnt lgkmcnt(6)
	v_pk_mul_f32 v[28:29], v[58:59], v[36:37] op_sel_hi:[1,0]
	v_pk_fma_f32 v[28:29], v[60:61], v[36:37], v[28:29] op_sel:[0,1,0]
	v_pk_fma_f32 v[28:29], v[62:63], v[38:39], v[28:29] op_sel_hi:[1,0,1]
	v_pk_fma_f32 v[28:29], v[64:65], v[38:39], v[28:29] op_sel:[0,1,0]
	v_pk_mul_f32 v[66:67], v[58:59], v[40:41] op_sel_hi:[1,0]
	v_pk_mul_f32 v[68:69], v[60:61], v[40:41] op_sel:[0,1]
	v_add_f32_dpp v28, v28, v28 quad_perm:[1,0,3,2] row_mask:0xf bank_mask:0xf bound_ctrl:1
	v_add_f32_dpp v29, v29, v29 quad_perm:[1,0,3,2] row_mask:0xf bank_mask:0xf bound_ctrl:1
	v_pk_mul_f32 v[70:71], v[62:63], v[42:43] op_sel_hi:[1,0]
	v_add_f32_dpp v28, v28, v28 quad_perm:[2,3,0,1] row_mask:0xf bank_mask:0xf bound_ctrl:1
	v_add_f32_dpp v29, v29, v29 quad_perm:[2,3,0,1] row_mask:0xf bank_mask:0xf bound_ctrl:1
	v_pk_mul_f32 v[72:73], v[64:65], v[42:43] op_sel:[0,1]
	v_add_f32_dpp v28, v28, v28 row_half_mirror row_mask:0xf bank_mask:0xf bound_ctrl:1
	v_add_f32_dpp v29, v29, v29 row_half_mirror row_mask:0xf bank_mask:0xf bound_ctrl:1
	v_pk_fma_f32 v[66:67], v[56:57], v[48:49], v[66:67] op_sel_hi:[1,0,1]
	v_add_f32_dpp v28, v28, v28 row_mirror row_mask:0xf bank_mask:0xf bound_ctrl:1
	v_add_f32_dpp v29, v29, v29 row_mirror row_mask:0xf bank_mask:0xf bound_ctrl:1
	v_pk_fma_f32 v[68:69], v[56:57], v[48:49], v[68:69] op_sel:[0,1,0]
	v_pk_fma_f32 v[70:71], v[56:57], v[50:51], v[70:71] op_sel_hi:[1,0,1]
	v_pk_fma_f32 v[72:73], v[56:57], v[50:51], v[72:73] op_sel:[0,1,0]
	v_pk_fma_f32 v[58:59], v[28:29], v[44:45], v[66:67] op_sel_hi:[1,0,1] neg_lo:[1,0,0] neg_hi:[1,0,0]
	v_pk_fma_f32 v[60:61], v[28:29], v[44:45], v[68:69] op_sel:[0,1,0] neg_lo:[1,0,0] neg_hi:[1,0,0]
	v_pk_fma_f32 v[62:63], v[28:29], v[46:47], v[70:71] op_sel_hi:[1,0,1] neg_lo:[1,0,0] neg_hi:[1,0,0]
	v_pk_fma_f32 v[64:65], v[28:29], v[46:47], v[72:73] op_sel:[0,1,0] neg_lo:[1,0,0] neg_hi:[1,0,0]
	v_pk_mul_f32 v[92:93], v[58:59], v[52:53] op_sel_hi:[1,0]
	v_pk_fma_f32 v[92:93], v[60:61], v[52:53], v[92:93] op_sel:[0,1,0]
	v_pk_fma_f32 v[92:93], v[62:63], v[54:55], v[92:93] op_sel_hi:[1,0,1]
	v_pk_fma_f32 v[92:93], v[64:65], v[54:55], v[92:93] op_sel:[0,1,0]
	ds_read_b128 v[36:39], v3 offset:15104
	ds_read_b128 v[40:43], v3 offset:23296
	ds_read_b64 v[56:57], v34 offset:6912
	ds_read_b128 v[48:51], v3 offset:11008
	ds_read_b128 v[44:47], v3 offset:19200
	ds_read_b128 v[52:55], v3 offset:2816
	s_waitcnt lgkmcnt(6)
; template <int RB, int EK, int D> __device__ __forceinline__ void rwkv_item_ws(const Params& p, int j, int s, int hd, int rq, char* shm_) {
;     ...
;       auto ld = [&](int stp, f32x2* kk_, f32x2* w_, f32x2* b_, f32x2* k2_, f32x2* r_, float* vv_) {
;         int t = d == 0 ? stp : CH - 1 - stp;
;         int o = t * 64 + kq * EK;
; #pragma unroll
;         for (int e = 0; e < NP; ++e) {
;           kk_[e] = *reinterpret_cast<const f32x2*>(skk + o + 2 * e);
;           w_[e] = *reinterpret_cast<const f32x2*>(sw + o + 2 * e);
;           b_[e] = *reinterpret_cast<const f32x2*>(sb + o + 2 * e);
;           k2_[e] = *reinterpret_cast<const f32x2*>(sk + o + 2 * e);
;           r_[e] = *reinterpret_cast<const f32x2*>(sr + o + 2 * e);
;         }
; #pragma unroll
;         for (int rb = 0; rb < RB; ++rb) vv_[rb] = sv[t * 64 + row0 + rb];
;       };
;       ld(0, kkc_, wc_, bc_, k2c_, rc_, vvc);
;       float ys[CH][RB];
; #pragma unroll
;       for (int stp = 0; stp < CH; ++stp) {
;         f32x2 kkn_[NP], wn_[NP], bn_[NP], k2n_[NP], rn_[NP];
;         float vvn[RB];
;         ld(stp < CH - 1 ? stp + 1 : CH - 1, kkn_, wn_, bn_, k2n_, rn_, vvn);
; #pragma unroll
;         for (int rb = 0; rb < RB; ++rb) {
;           f32x2 acc2 = S[rb][0] * kkc_[0] + S[rb][1] * kkc_[1];
;           if constexpr (NP == 4) acc2 += S[rb][2] * kkc_[2] + S[rb][3] * kkc_[3];
;           float sa = reduce_row<LPR>(-(acc2[0] + acc2[1]));
;           f32x2 sa2 = {sa, sa}, vv2 = {vvc[rb], vvc[rb]};
; #pragma unroll
;           for (int e = 0; e < NP; ++e) S[rb][e] = S[rb][e] * wc_[e] + sa2 * bc_[e] + vv2 * k2c_[e];
;           f32x2 y2 = S[rb][0] * rc_[0] + S[rb][1] * rc_[1];
;           if constexpr (NP == 4) y2 += S[rb][2] * rc_[2] + S[rb][3] * rc_[3];
;           ys[stp][rb] = reduce_row<LPR>(y2[0] + y2[1]);
;         }
	v_pk_mul_f32 v[28:29], v[58:59], v[6:7] op_sel_hi:[1,0]
	v_pk_fma_f32 v[28:29], v[60:61], v[6:7], v[28:29] op_sel:[0,1,0]
	v_pk_fma_f32 v[28:29], v[62:63], v[8:9], v[28:29] op_sel_hi:[1,0,1]
	v_pk_fma_f32 v[28:29], v[64:65], v[8:9], v[28:29] op_sel:[0,1,0]
	v_pk_mul_f32 v[66:67], v[58:59], v[10:11] op_sel_hi:[1,0]
	v_pk_mul_f32 v[68:69], v[60:61], v[10:11] op_sel:[0,1]
	v_add_f32_dpp v28, v28, v28 quad_perm:[1,0,3,2] row_mask:0xf bank_mask:0xf bound_ctrl:1
	v_add_f32_dpp v29, v29, v29 quad_perm:[1,0,3,2] row_mask:0xf bank_mask:0xf bound_ctrl:1
	v_pk_mul_f32 v[70:71], v[62:63], v[12:13] op_sel_hi:[1,0]
	v_add_f32_dpp v28, v28, v28 quad_perm:[2,3,0,1] row_mask:0xf bank_mask:0xf bound_ctrl:1
	v_add_f32_dpp v29, v29, v29 quad_perm:[2,3,0,1] row_mask:0xf bank_mask:0xf bound_ctrl:1
	v_pk_mul_f32 v[72:73], v[64:65], v[12:13] op_sel:[0,1]
	v_add_f32_dpp v28, v28, v28 row_half_mirror row_mask:0xf bank_mask:0xf bound_ctrl:1
	v_add_f32_dpp v29, v29, v29 row_half_mirror row_mask:0xf bank_mask:0xf bound_ctrl:1
	v_pk_fma_f32 v[66:67], v[26:27], v[18:19], v[66:67] op_sel_hi:[1,0,1]
	v_add_f32_dpp v28, v28, v28 row_mirror row_mask:0xf bank_mask:0xf bound_ctrl:1
	v_add_f32_dpp v29, v29, v29 row_mirror row_mask:0xf bank_mask:0xf bound_ctrl:1
	v_pk_fma_f32 v[68:69], v[26:27], v[18:19], v[68:69] op_sel:[0,1,0]
	v_pk_fma_f32 v[70:71], v[26:27], v[20:21], v[70:71] op_sel_hi:[1,0,1]
	v_pk_fma_f32 v[72:73], v[26:27], v[20:21], v[72:73] op_sel:[0,1,0]
	v_pk_fma_f32 v[58:59], v[28:29], v[14:15], v[66:67] op_sel_hi:[1,0,1] neg_lo:[1,0,0] neg_hi:[1,0,0]
	v_pk_fma_f32 v[60:61], v[28:29], v[14:15], v[68:69] op_sel:[0,1,0] neg_lo:[1,0,0] neg_hi:[1,0,0]
	v_pk_fma_f32 v[62:63], v[28:29], v[16:17], v[70:71] op_sel_hi:[1,0,1] neg_lo:[1,0,0] neg_hi:[1,0,0]
	v_pk_fma_f32 v[64:65], v[28:29], v[16:17], v[72:73] op_sel:[0,1,0] neg_lo:[1,0,0] neg_hi:[1,0,0]
	v_pk_mul_f32 v[94:95], v[58:59], v[22:23] op_sel_hi:[1,0]
	v_pk_fma_f32 v[94:95], v[60:61], v[22:23], v[94:95] op_sel:[0,1,0]
	v_pk_fma_f32 v[94:95], v[62:63], v[24:25], v[94:95] op_sel_hi:[1,0,1]
	v_pk_fma_f32 v[94:95], v[64:65], v[24:25], v[94:95] op_sel:[0,1,0]
	ds_read_b128 v[6:9], v3 offset:15360
	ds_read_b128 v[10:13], v3 offset:23552
	ds_read_b64 v[26:27], v34 offset:7168
	ds_read_b128 v[18:21], v3 offset:11264
	ds_read_b128 v[14:17], v3 offset:19456
	ds_read_b128 v[22:25], v3 offset:3072
	s_waitcnt lgkmcnt(6)
	v_pk_mul_f32 v[28:29], v[58:59], v[36:37] op_sel_hi:[1,0]
	v_pk_fma_f32 v[28:29], v[60:61], v[36:37], v[28:29] op_sel:[0,1,0]
	v_pk_fma_f32 v[28:29], v[62:63], v[38:39], v[28:29] op_sel_hi:[1,0,1]
	v_pk_fma_f32 v[28:29], v[64:65], v[38:39], v[28:29] op_sel:[0,1,0]
	v_pk_mul_f32 v[66:67], v[58:59], v[40:41] op_sel_hi:[1,0]
	v_pk_mul_f32 v[68:69], v[60:61], v[40:41] op_sel:[0,1]
	v_add_f32_dpp v28, v28, v28 quad_perm:[1,0,3,2] row_mask:0xf bank_mask:0xf bound_ctrl:1
	v_add_f32_dpp v29, v29, v29 quad_perm:[1,0,3,2] row_mask:0xf bank_mask:0xf bound_ctrl:1
	v_pk_mul_f32 v[70:71], v[62:63], v[42:43] op_sel_hi:[1,0]
	v_add_f32_dpp v28, v28, v28 quad_perm:[2,3,0,1] row_mask:0xf bank_mask:0xf bound_ctrl:1
	v_add_f32_dpp v29, v29, v29 quad_perm:[2,3,0,1] row_mask:0xf bank_mask:0xf bound_ctrl:1
	v_pk_mul_f32 v[72:73], v[64:65], v[42:43] op_sel:[0,1]
	v_add_f32_dpp v28, v28, v28 row_half_mirror row_mask:0xf bank_mask:0xf bound_ctrl:1
	v_add_f32_dpp v29, v29, v29 row_half_mirror row_mask:0xf bank_mask:0xf bound_ctrl:1
	v_pk_fma_f32 v[66:67], v[56:57], v[48:49], v[66:67] op_sel_hi:[1,0,1]
	v_add_f32_dpp v28, v28, v28 row_mirror row_mask:0xf bank_mask:0xf bound_ctrl:1
	v_add_f32_dpp v29, v29, v29 row_mirror row_mask:0xf bank_mask:0xf bound_ctrl:1
	v_pk_fma_f32 v[68:69], v[56:57], v[48:49], v[68:69] op_sel:[0,1,0]
	v_pk_fma_f32 v[70:71], v[56:57], v[50:51], v[70:71] op_sel_hi:[1,0,1]
	v_pk_fma_f32 v[72:73], v[56:57], v[50:51], v[72:73] op_sel:[0,1,0]
	v_pk_fma_f32 v[58:59], v[28:29], v[44:45], v[66:67] op_sel_hi:[1,0,1] neg_lo:[1,0,0] neg_hi:[1,0,0]
	v_pk_fma_f32 v[60:61], v[28:29], v[44:45], v[68:69] op_sel:[0,1,0] neg_lo:[1,0,0] neg_hi:[1,0,0]
	v_pk_fma_f32 v[62:63], v[28:29], v[46:47], v[70:71] op_sel_hi:[1,0,1] neg_lo:[1,0,0] neg_hi:[1,0,0]
	v_pk_fma_f32 v[64:65], v[28:29], v[46:47], v[72:73] op_sel:[0,1,0] neg_lo:[1,0,0] neg_hi:[1,0,0]
	v_pk_mul_f32 v[96:97], v[58:59], v[52:53] op_sel_hi:[1,0]
	v_pk_fma_f32 v[96:97], v[60:61], v[52:53], v[96:97] op_sel:[0,1,0]
	v_pk_fma_f32 v[96:97], v[62:63], v[54:55], v[96:97] op_sel_hi:[1,0,1]
	v_pk_fma_f32 v[96:97], v[64:65], v[54:55], v[96:97] op_sel:[0,1,0]
	ds_read_b128 v[36:39], v3 offset:15616
	ds_read_b128 v[40:43], v3 offset:23808
	ds_read_b64 v[56:57], v34 offset:7424
	ds_read_b128 v[48:51], v3 offset:11520
	ds_read_b128 v[44:47], v3 offset:19712
	ds_read_b128 v[52:55], v3 offset:3328
	s_waitcnt lgkmcnt(6)
; template <int RB, int EK, int D> __device__ __forceinline__ void rwkv_item_ws(const Params& p, int j, int s, int hd, int rq, char* shm_) {
;     ...
;       auto ld = [&](int stp, f32x2* kk_, f32x2* w_, f32x2* b_, f32x2* k2_, f32x2* r_, float* vv_) {
;         int t = d == 0 ? stp : CH - 1 - stp;
;         int o = t * 64 + kq * EK;
; #pragma unroll
;         for (int e = 0; e < NP; ++e) {
;           kk_[e] = *reinterpret_cast<const f32x2*>(skk + o + 2 * e);
;           w_[e] = *reinterpret_cast<const f32x2*>(sw + o + 2 * e);
;           b_[e] = *reinterpret_cast<const f32x2*>(sb + o + 2 * e);
;           k2_[e] = *reinterpret_cast<const f32x2*>(sk + o + 2 * e);
;           r_[e] = *reinterpret_cast<const f32x2*>(sr + o + 2 * e);
;         }
; #pragma unroll
;         for (int rb = 0; rb < RB; ++rb) vv_[rb] = sv[t * 64 + row0 + rb];
;       };
;       ld(0, kkc_, wc_, bc_, k2c_, rc_, vvc);
;       float ys[CH][RB];
; #pragma unroll
;       for (int stp = 0; stp < CH; ++stp) {
;         f32x2 kkn_[NP], wn_[NP], bn_[NP], k2n_[NP], rn_[NP];
;         float vvn[RB];
;         ld(stp < CH - 1 ? stp + 1 : CH - 1, kkn_, wn_, bn_, k2n_, rn_, vvn);
; #pragma unroll
;         for (int rb = 0; rb < RB; ++rb) {
;           f32x2 acc2 = S[rb][0] * kkc_[0] + S[rb][1] * kkc_[1];
;           if constexpr (NP == 4) acc2 += S[rb][2] * kkc_[2] + S[rb][3] * kkc_[3];
;           float sa = reduce_row<LPR>(-(acc2[0] + acc2[1]));
;           f32x2 sa2 = {sa, sa}, vv2 = {vvc[rb], vvc[rb]};
; #pragma unroll
;           for (int e = 0; e < NP; ++e) S[rb][e] = S[rb][e] * wc_[e] + sa2 * bc_[e] + vv2 * k2c_[e];
;           f32x2 y2 = S[rb][0] * rc_[0] + S[rb][1] * rc_[1];
;           if constexpr (NP == 4) y2 += S[rb][2] * rc_[2] + S[rb][3] * rc_[3];
;           ys[stp][rb] = reduce_row<LPR>(y2[0] + y2[1]);
;         }
	v_pk_mul_f32 v[28:29], v[58:59], v[6:7] op_sel_hi:[1,0]
	v_pk_fma_f32 v[28:29], v[60:61], v[6:7], v[28:29] op_sel:[0,1,0]
	v_pk_fma_f32 v[28:29], v[62:63], v[8:9], v[28:29] op_sel_hi:[1,0,1]
	v_pk_fma_f32 v[28:29], v[64:65], v[8:9], v[28:29] op_sel:[0,1,0]
	v_pk_mul_f32 v[66:67], v[58:59], v[10:11] op_sel_hi:[1,0]
	v_pk_mul_f32 v[68:69], v[60:61], v[10:11] op_sel:[0,1]
	v_add_f32_dpp v28, v28, v28 quad_perm:[1,0,3,2] row_mask:0xf bank_mask:0xf bound_ctrl:1
	v_add_f32_dpp v29, v29, v29 quad_perm:[1,0,3,2] row_mask:0xf bank_mask:0xf bound_ctrl:1
	v_pk_mul_f32 v[70:71], v[62:63], v[12:13] op_sel_hi:[1,0]
	v_add_f32_dpp v28, v28, v28 quad_perm:[2,3,0,1] row_mask:0xf bank_mask:0xf bound_ctrl:1
	v_add_f32_dpp v29, v29, v29 quad_perm:[2,3,0,1] row_mask:0xf bank_mask:0xf bound_ctrl:1
	v_pk_mul_f32 v[72:73], v[64:65], v[12:13] op_sel:[0,1]
	v_add_f32_dpp v28, v28, v28 row_half_mirror row_mask:0xf bank_mask:0xf bound_ctrl:1
	v_add_f32_dpp v29, v29, v29 row_half_mirror row_mask:0xf bank_mask:0xf bound_ctrl:1
	v_pk_fma_f32 v[66:67], v[26:27], v[18:19], v[66:67] op_sel_hi:[1,0,1]
	v_add_f32_dpp v28, v28, v28 row_mirror row_mask:0xf bank_mask:0xf bound_ctrl:1
	v_add_f32_dpp v29, v29, v29 row_mirror row_mask:0xf bank_mask:0xf bound_ctrl:1
	v_pk_fma_f32 v[68:69], v[26:27], v[18:19], v[68:69] op_sel:[0,1,0]
	v_pk_fma_f32 v[70:71], v[26:27], v[20:21], v[70:71] op_sel_hi:[1,0,1]
	v_pk_fma_f32 v[72:73], v[26:27], v[20:21], v[72:73] op_sel:[0,1,0]
	v_pk_fma_f32 v[58:59], v[28:29], v[14:15], v[66:67] op_sel_hi:[1,0,1] neg_lo:[1,0,0] neg_hi:[1,0,0]
	v_pk_fma_f32 v[60:61], v[28:29], v[14:15], v[68:69] op_sel:[0,1,0] neg_lo:[1,0,0] neg_hi:[1,0,0]
	v_pk_fma_f32 v[62:63], v[28:29], v[16:17], v[70:71] op_sel_hi:[1,0,1] neg_lo:[1,0,0] neg_hi:[1,0,0]
	v_pk_fma_f32 v[64:65], v[28:29], v[16:17], v[72:73] op_sel:[0,1,0] neg_lo:[1,0,0] neg_hi:[1,0,0]
	v_pk_mul_f32 v[98:99], v[58:59], v[22:23] op_sel_hi:[1,0]
	v_pk_fma_f32 v[98:99], v[60:61], v[22:23], v[98:99] op_sel:[0,1,0]
	v_pk_fma_f32 v[98:99], v[62:63], v[24:25], v[98:99] op_sel_hi:[1,0,1]
	v_pk_fma_f32 v[98:99], v[64:65], v[24:25], v[98:99] op_sel:[0,1,0]
	ds_read_b128 v[6:9], v3 offset:15872
	ds_read_b128 v[10:13], v3 offset:24064
	ds_read_b64 v[26:27], v34 offset:7680
	ds_read_b128 v[18:21], v3 offset:11776
	ds_read_b128 v[14:17], v3 offset:19968
	ds_read_b128 v[22:25], v3 offset:3584
	s_waitcnt lgkmcnt(6)
	v_pk_mul_f32 v[28:29], v[58:59], v[36:37] op_sel_hi:[1,0]
	v_pk_fma_f32 v[28:29], v[60:61], v[36:37], v[28:29] op_sel:[0,1,0]
	v_pk_fma_f32 v[28:29], v[62:63], v[38:39], v[28:29] op_sel_hi:[1,0,1]
	v_pk_fma_f32 v[28:29], v[64:65], v[38:39], v[28:29] op_sel:[0,1,0]
	v_pk_mul_f32 v[66:67], v[58:59], v[40:41] op_sel_hi:[1,0]
	v_pk_mul_f32 v[68:69], v[60:61], v[40:41] op_sel:[0,1]
	v_add_f32_dpp v28, v28, v28 quad_perm:[1,0,3,2] row_mask:0xf bank_mask:0xf bound_ctrl:1
	v_add_f32_dpp v29, v29, v29 quad_perm:[1,0,3,2] row_mask:0xf bank_mask:0xf bound_ctrl:1
	v_pk_mul_f32 v[70:71], v[62:63], v[42:43] op_sel_hi:[1,0]
	v_add_f32_dpp v28, v28, v28 quad_perm:[2,3,0,1] row_mask:0xf bank_mask:0xf bound_ctrl:1
	v_add_f32_dpp v29, v29, v29 quad_perm:[2,3,0,1] row_mask:0xf bank_mask:0xf bound_ctrl:1
	v_pk_mul_f32 v[72:73], v[64:65], v[42:43] op_sel:[0,1]
	v_add_f32_dpp v28, v28, v28 row_half_mirror row_mask:0xf bank_mask:0xf bound_ctrl:1
	v_add_f32_dpp v29, v29, v29 row_half_mirror row_mask:0xf bank_mask:0xf bound_ctrl:1
	v_pk_fma_f32 v[66:67], v[56:57], v[48:49], v[66:67] op_sel_hi:[1,0,1]
	v_add_f32_dpp v28, v28, v28 row_mirror row_mask:0xf bank_mask:0xf bound_ctrl:1
	v_add_f32_dpp v29, v29, v29 row_mirror row_mask:0xf bank_mask:0xf bound_ctrl:1
	v_pk_fma_f32 v[68:69], v[56:57], v[48:49], v[68:69] op_sel:[0,1,0]
	v_pk_fma_f32 v[70:71], v[56:57], v[50:51], v[70:71] op_sel_hi:[1,0,1]
	v_pk_fma_f32 v[72:73], v[56:57], v[50:51], v[72:73] op_sel:[0,1,0]
	v_pk_fma_f32 v[58:59], v[28:29], v[44:45], v[66:67] op_sel_hi:[1,0,1] neg_lo:[1,0,0] neg_hi:[1,0,0]
	v_pk_fma_f32 v[60:61], v[28:29], v[44:45], v[68:69] op_sel:[0,1,0] neg_lo:[1,0,0] neg_hi:[1,0,0]
	v_pk_fma_f32 v[62:63], v[28:29], v[46:47], v[70:71] op_sel_hi:[1,0,1] neg_lo:[1,0,0] neg_hi:[1,0,0]
	v_pk_fma_f32 v[64:65], v[28:29], v[46:47], v[72:73] op_sel:[0,1,0] neg_lo:[1,0,0] neg_hi:[1,0,0]
	v_pk_mul_f32 v[100:101], v[58:59], v[52:53] op_sel_hi:[1,0]
	v_pk_fma_f32 v[100:101], v[60:61], v[52:53], v[100:101] op_sel:[0,1,0]
	v_pk_fma_f32 v[100:101], v[62:63], v[54:55], v[100:101] op_sel_hi:[1,0,1]
	v_pk_fma_f32 v[100:101], v[64:65], v[54:55], v[100:101] op_sel:[0,1,0]
	ds_read_b128 v[36:39], v3 offset:16128
	ds_read_b128 v[40:43], v3 offset:24320
	ds_read_b64 v[56:57], v34 offset:7936
	ds_read_b128 v[48:51], v3 offset:12032
	ds_read_b128 v[44:47], v3 offset:20224
	ds_read_b128 v[52:55], v3 offset:3840
	s_waitcnt lgkmcnt(6)
; template <int RB, int EK, int D> __device__ __forceinline__ void rwkv_item_ws(const Params& p, int j, int s, int hd, int rq, char* shm_) {
;     ...
;       for (int stp = 0; stp < CH; ++stp) {
;         f32x2 kkn_[NP], wn_[NP], bn_[NP], k2n_[NP], rn_[NP];
;         float vvn[RB];
;         ld(stp < CH - 1 ? stp + 1 : CH - 1, kkn_, wn_, bn_, k2n_, rn_, vvn);
; #pragma unroll
;         for (int rb = 0; rb < RB; ++rb) {
;           f32x2 acc2 = S[rb][0] * kkc_[0] + S[rb][1] * kkc_[1];
;           if constexpr (NP == 4) acc2 += S[rb][2] * kkc_[2] + S[rb][3] * kkc_[3];
;           float sa = reduce_row<LPR>(-(acc2[0] + acc2[1]));
;           f32x2 sa2 = {sa, sa}, vv2 = {vvc[rb], vvc[rb]};
; #pragma unroll
;           for (int e = 0; e < NP; ++e) S[rb][e] = S[rb][e] * wc_[e] + sa2 * bc_[e] + vv2 * k2c_[e];
;           f32x2 y2 = S[rb][0] * rc_[0] + S[rb][1] * rc_[1];
;           if constexpr (NP == 4) y2 += S[rb][2] * rc_[2] + S[rb][3] * rc_[3];
;           ys[stp][rb] = reduce_row<LPR>(y2[0] + y2[1]);
	v_pk_mul_f32 v[28:29], v[58:59], v[6:7] op_sel_hi:[1,0]
	v_pk_fma_f32 v[28:29], v[60:61], v[6:7], v[28:29] op_sel:[0,1,0]
	v_pk_fma_f32 v[28:29], v[62:63], v[8:9], v[28:29] op_sel_hi:[1,0,1]
	v_pk_fma_f32 v[28:29], v[64:65], v[8:9], v[28:29] op_sel:[0,1,0]
	v_pk_mul_f32 v[66:67], v[58:59], v[10:11] op_sel_hi:[1,0]
	v_pk_mul_f32 v[68:69], v[60:61], v[10:11] op_sel:[0,1]
	v_add_f32_dpp v28, v28, v28 quad_perm:[1,0,3,2] row_mask:0xf bank_mask:0xf bound_ctrl:1
	v_add_f32_dpp v29, v29, v29 quad_perm:[1,0,3,2] row_mask:0xf bank_mask:0xf bound_ctrl:1
	v_pk_mul_f32 v[70:71], v[62:63], v[12:13] op_sel_hi:[1,0]
	v_add_f32_dpp v28, v28, v28 quad_perm:[2,3,0,1] row_mask:0xf bank_mask:0xf bound_ctrl:1
	v_add_f32_dpp v29, v29, v29 quad_perm:[2,3,0,1] row_mask:0xf bank_mask:0xf bound_ctrl:1
	v_pk_mul_f32 v[72:73], v[64:65], v[12:13] op_sel:[0,1]
	v_add_f32_dpp v28, v28, v28 row_half_mirror row_mask:0xf bank_mask:0xf bound_ctrl:1
	v_add_f32_dpp v29, v29, v29 row_half_mirror row_mask:0xf bank_mask:0xf bound_ctrl:1
	v_pk_fma_f32 v[66:67], v[26:27], v[18:19], v[66:67] op_sel_hi:[1,0,1]
	v_add_f32_dpp v28, v28, v28 row_mirror row_mask:0xf bank_mask:0xf bound_ctrl:1
	v_add_f32_dpp v29, v29, v29 row_mirror row_mask:0xf bank_mask:0xf bound_ctrl:1
	v_pk_fma_f32 v[68:69], v[26:27], v[18:19], v[68:69] op_sel:[0,1,0]
	v_pk_fma_f32 v[70:71], v[26:27], v[20:21], v[70:71] op_sel_hi:[1,0,1]
	v_pk_fma_f32 v[72:73], v[26:27], v[20:21], v[72:73] op_sel:[0,1,0]
	v_pk_fma_f32 v[58:59], v[28:29], v[14:15], v[66:67] op_sel_hi:[1,0,1] neg_lo:[1,0,0] neg_hi:[1,0,0]
	v_pk_fma_f32 v[60:61], v[28:29], v[14:15], v[68:69] op_sel:[0,1,0] neg_lo:[1,0,0] neg_hi:[1,0,0]
	v_pk_fma_f32 v[62:63], v[28:29], v[16:17], v[70:71] op_sel_hi:[1,0,1] neg_lo:[1,0,0] neg_hi:[1,0,0]
	v_pk_fma_f32 v[64:65], v[28:29], v[16:17], v[72:73] op_sel:[0,1,0] neg_lo:[1,0,0] neg_hi:[1,0,0]
	v_pk_mul_f32 v[102:103], v[58:59], v[22:23] op_sel_hi:[1,0]
	v_pk_fma_f32 v[102:103], v[60:61], v[22:23], v[102:103] op_sel:[0,1,0]
	v_pk_fma_f32 v[102:103], v[62:63], v[24:25], v[102:103] op_sel_hi:[1,0,1]
	v_pk_fma_f32 v[102:103], v[64:65], v[24:25], v[102:103] op_sel:[0,1,0]
	s_waitcnt lgkmcnt(0)
	v_pk_mul_f32 v[28:29], v[58:59], v[36:37] op_sel_hi:[1,0]
	v_pk_fma_f32 v[28:29], v[60:61], v[36:37], v[28:29] op_sel:[0,1,0]
	v_pk_fma_f32 v[28:29], v[62:63], v[38:39], v[28:29] op_sel_hi:[1,0,1]
	v_pk_fma_f32 v[28:29], v[64:65], v[38:39], v[28:29] op_sel:[0,1,0]
	v_pk_mul_f32 v[66:67], v[58:59], v[40:41] op_sel_hi:[1,0]
	v_pk_mul_f32 v[68:69], v[60:61], v[40:41] op_sel:[0,1]
	v_add_f32_dpp v28, v28, v28 quad_perm:[1,0,3,2] row_mask:0xf bank_mask:0xf bound_ctrl:1
	v_add_f32_dpp v29, v29, v29 quad_perm:[1,0,3,2] row_mask:0xf bank_mask:0xf bound_ctrl:1
	v_pk_mul_f32 v[70:71], v[62:63], v[42:43] op_sel_hi:[1,0]
	v_add_f32_dpp v28, v28, v28 quad_perm:[2,3,0,1] row_mask:0xf bank_mask:0xf bound_ctrl:1
	v_add_f32_dpp v29, v29, v29 quad_perm:[2,3,0,1] row_mask:0xf bank_mask:0xf bound_ctrl:1
	v_pk_mul_f32 v[72:73], v[64:65], v[42:43] op_sel:[0,1]
	v_add_f32_dpp v28, v28, v28 row_half_mirror row_mask:0xf bank_mask:0xf bound_ctrl:1
	v_add_f32_dpp v29, v29, v29 row_half_mirror row_mask:0xf bank_mask:0xf bound_ctrl:1
	v_pk_fma_f32 v[66:67], v[56:57], v[48:49], v[66:67] op_sel_hi:[1,0,1]
	v_add_f32_dpp v28, v28, v28 row_mirror row_mask:0xf bank_mask:0xf bound_ctrl:1
	v_add_f32_dpp v29, v29, v29 row_mirror row_mask:0xf bank_mask:0xf bound_ctrl:1
	v_pk_fma_f32 v[68:69], v[56:57], v[48:49], v[68:69] op_sel:[0,1,0]
	v_pk_fma_f32 v[70:71], v[56:57], v[50:51], v[70:71] op_sel_hi:[1,0,1]
	v_pk_fma_f32 v[72:73], v[56:57], v[50:51], v[72:73] op_sel:[0,1,0]
	v_pk_fma_f32 v[58:59], v[28:29], v[44:45], v[66:67] op_sel_hi:[1,0,1] neg_lo:[1,0,0] neg_hi:[1,0,0]
	v_pk_fma_f32 v[60:61], v[28:29], v[44:45], v[68:69] op_sel:[0,1,0] neg_lo:[1,0,0] neg_hi:[1,0,0]
	v_pk_fma_f32 v[62:63], v[28:29], v[46:47], v[70:71] op_sel_hi:[1,0,1] neg_lo:[1,0,0] neg_hi:[1,0,0]
	v_pk_fma_f32 v[64:65], v[28:29], v[46:47], v[72:73] op_sel:[0,1,0] neg_lo:[1,0,0] neg_hi:[1,0,0]
	v_pk_mul_f32 v[104:105], v[58:59], v[52:53] op_sel_hi:[1,0]
	v_pk_fma_f32 v[104:105], v[60:61], v[52:53], v[104:105] op_sel:[0,1,0]
	v_pk_fma_f32 v[104:105], v[62:63], v[54:55], v[104:105] op_sel_hi:[1,0,1]
	v_pk_fma_f32 v[104:105], v[64:65], v[54:55], v[104:105] op_sel:[0,1,0]
	v_add_f32_dpp v74, v74, v74 row_half_mirror row_mask:0xf bank_mask:0x5 bound_ctrl:1
	v_add_f32_dpp v76, v76, v76 row_half_mirror row_mask:0xf bank_mask:0x5 bound_ctrl:1
	v_add_f32_dpp v74, v75, v75 row_half_mirror row_mask:0xf bank_mask:0xa bound_ctrl:1
	v_add_f32_dpp v76, v77, v77 row_half_mirror row_mask:0xf bank_mask:0xa bound_ctrl:1
	v_add_f32_dpp v78, v78, v78 row_half_mirror row_mask:0xf bank_mask:0x5 bound_ctrl:1
	v_add_f32_dpp v80, v80, v80 row_half_mirror row_mask:0xf bank_mask:0x5 bound_ctrl:1
	v_add_f32_dpp v78, v79, v79 row_half_mirror row_mask:0xf bank_mask:0xa bound_ctrl:1
	v_add_f32_dpp v80, v81, v81 row_half_mirror row_mask:0xf bank_mask:0xa bound_ctrl:1
	v_add_f32_dpp v82, v82, v82 row_half_mirror row_mask:0xf bank_mask:0x5 bound_ctrl:1
	v_add_f32_dpp v84, v84, v84 row_half_mirror row_mask:0xf bank_mask:0x5 bound_ctrl:1
	v_add_f32_dpp v82, v83, v83 row_half_mirror row_mask:0xf bank_mask:0xa bound_ctrl:1
	v_add_f32_dpp v84, v85, v85 row_half_mirror row_mask:0xf bank_mask:0xa bound_ctrl:1
	v_add_f32_dpp v86, v86, v86 row_half_mirror row_mask:0xf bank_mask:0x5 bound_ctrl:1
	v_add_f32_dpp v88, v88, v88 row_half_mirror row_mask:0xf bank_mask:0x5 bound_ctrl:1
	v_add_f32_dpp v86, v87, v87 row_half_mirror row_mask:0xf bank_mask:0xa bound_ctrl:1
; template <int LPR> DEV float reduce_row(float x) {
;   x += dpp_f<0xB1>(x);
;   x += dpp_f<0x4E>(x);
;   x += dpp_f<0x141>(x);
;   if constexpr (LPR == 16) x += dpp_f<0x140>(x);
;   return x;
; template <int RB, int EK, int D> __device__ __forceinline__ void rwkv_item_ws(const Params& p, int j, int s, int hd, int rq, char* shm_) {
;     ...
;         for (int rb = 0; rb < RB; ++rb) {
;           f32x2 acc2 = S[rb][0] * kkc_[0] + S[rb][1] * kkc_[1];
;           if constexpr (NP == 4) acc2 += S[rb][2] * kkc_[2] + S[rb][3] * kkc_[3];
;           float sa = reduce_row<LPR>(-(acc2[0] + acc2[1]));
;           f32x2 sa2 = {sa, sa}, vv2 = {vvc[rb], vvc[rb]};
; #pragma unroll
;           for (int e = 0; e < NP; ++e) S[rb][e] = S[rb][e] * wc_[e] + sa2 * bc_[e] + vv2 * k2c_[e];
;           f32x2 y2 = S[rb][0] * rc_[0] + S[rb][1] * rc_[1];
;           if constexpr (NP == 4) y2 += S[rb][2] * rc_[2] + S[rb][3] * rc_[3];
;           ys[stp][rb] = reduce_row<LPR>(y2[0] + y2[1]);
;         }
; #pragma unroll
;         for (int e = 0; e < NP; ++e) { kkc_[e] = kkn_[e]; wc_[e] = wn_[e]; bc_[e] = bn_[e]; k2c_[e] = k2n_[e]; rc_[e] = rn_[e]; }
; #pragma unroll
;         for (int rb = 0; rb < RB; ++rb) vvc[rb] = vvn[rb];
;       }
;       if (kq == 0) {
; #pragma unroll
;         for (int stp = 0; stp < CH; ++stp) {
;           int t = d == 0 ? stp : CH - 1 - stp;
;           h16* yp = Y + (size_t)(st + chunk * CH + t) * 512 + hd * 64 + row0;
; #pragma unroll
;           for (int rb = 0; rb < RB; ++rb) yp[rb] = (h16)ys[stp][rb];
;         }
	v_add_f32_dpp v88, v89, v89 row_half_mirror row_mask:0xf bank_mask:0xa bound_ctrl:1
	v_add_f32_dpp v90, v90, v90 row_half_mirror row_mask:0xf bank_mask:0x5 bound_ctrl:1
	v_add_f32_dpp v92, v92, v92 row_half_mirror row_mask:0xf bank_mask:0x5 bound_ctrl:1
	v_add_f32_dpp v90, v91, v91 row_half_mirror row_mask:0xf bank_mask:0xa bound_ctrl:1
	v_add_f32_dpp v92, v93, v93 row_half_mirror row_mask:0xf bank_mask:0xa bound_ctrl:1
	v_add_f32_dpp v94, v94, v94 row_half_mirror row_mask:0xf bank_mask:0x5 bound_ctrl:1
	v_add_f32_dpp v96, v96, v96 row_half_mirror row_mask:0xf bank_mask:0x5 bound_ctrl:1
	v_add_f32_dpp v94, v95, v95 row_half_mirror row_mask:0xf bank_mask:0xa bound_ctrl:1
	v_add_f32_dpp v96, v97, v97 row_half_mirror row_mask:0xf bank_mask:0xa bound_ctrl:1
	v_add_f32_dpp v98, v98, v98 row_half_mirror row_mask:0xf bank_mask:0x5 bound_ctrl:1
	v_add_f32_dpp v100, v100, v100 row_half_mirror row_mask:0xf bank_mask:0x5 bound_ctrl:1
	v_add_f32_dpp v98, v99, v99 row_half_mirror row_mask:0xf bank_mask:0xa bound_ctrl:1
	v_add_f32_dpp v100, v101, v101 row_half_mirror row_mask:0xf bank_mask:0xa bound_ctrl:1
	v_add_f32_dpp v102, v102, v102 row_half_mirror row_mask:0xf bank_mask:0x5 bound_ctrl:1
	v_add_f32_dpp v104, v104, v104 row_half_mirror row_mask:0xf bank_mask:0x5 bound_ctrl:1
	v_add_f32_dpp v102, v103, v103 row_half_mirror row_mask:0xf bank_mask:0xa bound_ctrl:1
	v_add_f32_dpp v104, v105, v105 row_half_mirror row_mask:0xf bank_mask:0xa bound_ctrl:1
	v_add_f32_dpp v74, v74, v74 row_ror:8 row_mask:0xf bank_mask:0x3 bound_ctrl:1
	v_add_f32_dpp v78, v78, v78 row_ror:8 row_mask:0xf bank_mask:0x3 bound_ctrl:1
	v_add_f32_dpp v74, v76, v76 row_ror:8 row_mask:0xf bank_mask:0xc bound_ctrl:1
	v_add_f32_dpp v78, v80, v80 row_ror:8 row_mask:0xf bank_mask:0xc bound_ctrl:1
	v_add_f32_dpp v82, v82, v82 row_ror:8 row_mask:0xf bank_mask:0x3 bound_ctrl:1
	v_add_f32_dpp v86, v86, v86 row_ror:8 row_mask:0xf bank_mask:0x3 bound_ctrl:1
	v_add_f32_dpp v82, v84, v84 row_ror:8 row_mask:0xf bank_mask:0xc bound_ctrl:1
	v_add_f32_dpp v86, v88, v88 row_ror:8 row_mask:0xf bank_mask:0xc bound_ctrl:1
	v_add_f32_dpp v90, v90, v90 row_ror:8 row_mask:0xf bank_mask:0x3 bound_ctrl:1
	v_add_f32_dpp v94, v94, v94 row_ror:8 row_mask:0xf bank_mask:0x3 bound_ctrl:1
	v_add_f32_dpp v90, v92, v92 row_ror:8 row_mask:0xf bank_mask:0xc bound_ctrl:1
	v_add_f32_dpp v94, v96, v96 row_ror:8 row_mask:0xf bank_mask:0xc bound_ctrl:1
	v_add_f32_dpp v98, v98, v98 row_ror:8 row_mask:0xf bank_mask:0x3 bound_ctrl:1
	v_add_f32_dpp v102, v102, v102 row_ror:8 row_mask:0xf bank_mask:0x3 bound_ctrl:1
	v_add_f32_dpp v98, v100, v100 row_ror:8 row_mask:0xf bank_mask:0xc bound_ctrl:1
	v_add_f32_dpp v102, v104, v104 row_ror:8 row_mask:0xf bank_mask:0xc bound_ctrl:1
	v_add_f32_dpp v74, v74, v74 quad_perm:[1,0,3,2] row_mask:0xf bank_mask:0xf bound_ctrl:1
	v_add_f32_dpp v78, v78, v78 quad_perm:[1,0,3,2] row_mask:0xf bank_mask:0xf bound_ctrl:1
	v_add_f32_dpp v82, v82, v82 quad_perm:[1,0,3,2] row_mask:0xf bank_mask:0xf bound_ctrl:1
	v_add_f32_dpp v86, v86, v86 quad_perm:[1,0,3,2] row_mask:0xf bank_mask:0xf bound_ctrl:1
	v_add_f32_dpp v90, v90, v90 quad_perm:[1,0,3,2] row_mask:0xf bank_mask:0xf bound_ctrl:1
	v_add_f32_dpp v94, v94, v94 quad_perm:[1,0,3,2] row_mask:0xf bank_mask:0xf bound_ctrl:1
	v_add_f32_dpp v98, v98, v98 quad_perm:[1,0,3,2] row_mask:0xf bank_mask:0xf bound_ctrl:1
	v_add_f32_dpp v102, v102, v102 quad_perm:[1,0,3,2] row_mask:0xf bank_mask:0xf bound_ctrl:1
	v_add_f32_dpp v74, v74, v74 quad_perm:[2,3,0,1] row_mask:0xf bank_mask:0xf bound_ctrl:1
	v_add_f32_dpp v78, v78, v78 quad_perm:[2,3,0,1] row_mask:0xf bank_mask:0xf bound_ctrl:1
	v_add_f32_dpp v82, v82, v82 quad_perm:[2,3,0,1] row_mask:0xf bank_mask:0xf bound_ctrl:1
	v_add_f32_dpp v86, v86, v86 quad_perm:[2,3,0,1] row_mask:0xf bank_mask:0xf bound_ctrl:1
	v_add_f32_dpp v90, v90, v90 quad_perm:[2,3,0,1] row_mask:0xf bank_mask:0xf bound_ctrl:1
	v_add_f32_dpp v94, v94, v94 quad_perm:[2,3,0,1] row_mask:0xf bank_mask:0xf bound_ctrl:1
	v_add_f32_dpp v98, v98, v98 quad_perm:[2,3,0,1] row_mask:0xf bank_mask:0xf bound_ctrl:1
	v_add_f32_dpp v102, v102, v102 quad_perm:[2,3,0,1] row_mask:0xf bank_mask:0xf bound_ctrl:1
	v_and_b32_e32 v113, 12, v0
	v_cmp_eq_u32_e32 vcc, 0, v113
	v_lshrrev_b32_e32 v114, 4, v0
	v_and_b32_e32 v115, 1, v114
	v_lshlrev_b32_e32 v115, 1, v115
	v_lshrrev_b32_e32 v114, 1, v114
	v_mul_i32_i24_e32 v114, 1024, v114
	v_add_u32_e32 v114, v114, v115
	v_ashrrev_i32_e32 v115, 31, v114
	s_and_saveexec_b64 s[6:7], vcc
	s_cbranch_execz .LBB0_2099
	s_add_i32 s16, s4, -12
	s_ashr_i32 s17, s16, 31
	s_lshl_b64 s[16:17], s[16:17], 10
	v_lshl_add_u64 v[106:107], v[4:5], 0, s[16:17]
	v_lshl_add_u64 v[106:107], v[106:107], 0, v[114:115]
	s_add_i32 s16, s4, -4
	s_ashr_i32 s17, s16, 31
	s_lshl_b64 s[16:17], s[16:17], 10
	v_lshl_add_u64 v[108:109], v[4:5], 0, s[16:17]
	v_lshl_add_u64 v[108:109], v[108:109], 0, v[114:115]
	v_cvt_pk_f16_f32 v113, v74, v74
	global_store_short v[106:107], v113, off offset:-3072
	v_cvt_pk_f16_f32 v113, v78, v78
	global_store_short v[106:107], v113, off offset:-1024
	v_cvt_pk_f16_f32 v113, v82, v82
	global_store_short v[106:107], v113, off offset:1024
	v_cvt_pk_f16_f32 v113, v86, v86
	global_store_short v[106:107], v113, off offset:3072
	v_cvt_pk_f16_f32 v113, v90, v90
	global_store_short v[108:109], v113, off offset:-3072
	v_cvt_pk_f16_f32 v113, v94, v94
	global_store_short v[108:109], v113, off offset:-1024
	v_cvt_pk_f16_f32 v113, v98, v98
	global_store_short v[108:109], v113, off offset:1024
	v_cvt_pk_f16_f32 v113, v102, v102
	global_store_short v[108:109], v113, off offset:3072
	s_branch .LBB0_2099
